# grid barrier between P2 and P3 replaced by per-unit release/acquire flags (passA HU/HD stores write-through)
# baseline (speedup 1.0000x reference)
; __device__ __forceinline__ unsigned f2bf(float f) { return pk2(f, 0.f) & 0xffffu; }
; __device__ __forceinline__ void hgrn_passA(Frame& F, u32x2v* HU, float* HD) {
;     ...
;             for (int i = 0; i < 8; ++i)
; #pragma unroll
;                 for (int jj = 0; jj < 4; ++jj) { const int j = 4 * jh + jj; const float kk = 1.f - __expf(i > 0 ? lf[i][jh][jj] - lf[i - 1][jh][jj] : lf[i][jh][jj]);
;                     const float ev = kk * __expf(aend[jh][jj] - (off[jh][jj] + lf[i][jh][jj])); const unsigned bits = f2bf(ev);
;                     if (i & 1) ke[jj][i >> 1] |= bits << 16; else ke[jj][i >> 1] = bits; }
.LBB0_568:
	s_or_b64 exec, exec, s[0:1]
	v_add_f32_e32 v11, v96, v106
	v_mul_f32_e32 v10, 0x3fb8aa3b, v106
	v_sub_f32_e32 v11, v88, v11
	v_add_f32_e32 v13, v97, v107
	v_exp_f32_e32 v10, v10
	v_mul_f32_e32 v11, 0x3fb8aa3b, v11
	v_mul_f32_e32 v12, 0x3fb8aa3b, v107
	v_sub_f32_e32 v13, v89, v13
	v_exp_f32_e32 v11, v11
	v_exp_f32_e32 v12, v12
	v_mul_f32_e32 v13, 0x3fb8aa3b, v13
	v_exp_f32_e32 v13, v13
	v_sub_f32_e32 v10, 1.0, v10
	v_mul_f32_e32 v10, v10, v11
	v_sub_f32_e32 v11, 1.0, v12
	v_mul_f32_e32 v11, v11, v13
	v_add_f32_e32 v13, v90, v102
	v_mul_f32_e32 v12, 0x3fb8aa3b, v102
	v_sub_f32_e32 v13, v46, v13
	v_exp_f32_e32 v12, v12
	v_mul_f32_e32 v13, 0x3fb8aa3b, v13
	v_mul_f32_e32 v14, 0x3fb8aa3b, v103
	v_exp_f32_e32 v13, v13
	v_exp_f32_e32 v14, v14
	v_sub_f32_e32 v12, 1.0, v12
	v_sub_f32_e32 v15, v108, v106
	v_mul_f32_e32 v12, v12, v13
	v_sub_f32_e32 v13, 1.0, v14
	v_add_f32_e32 v14, v91, v103
	v_sub_f32_e32 v14, v47, v14
	v_add_f32_e32 v16, v108, v96
	v_mul_f32_e32 v14, 0x3fb8aa3b, v14
	v_mul_f32_e32 v15, 0x3fb8aa3b, v15
	v_sub_f32_e32 v16, v88, v16
	v_exp_f32_e32 v14, v14
	v_exp_f32_e32 v15, v15
	v_mul_f32_e32 v16, 0x3fb8aa3b, v16
	v_exp_f32_e32 v16, v16
	v_mul_f32_e32 v13, v13, v14
	v_sub_f32_e32 v14, 1.0, v15
	v_sub_f32_e32 v15, v109, v107
	v_mul_f32_e32 v14, v14, v16
	v_add_f32_e32 v16, v109, v97
	v_mul_f32_e32 v15, 0x3fb8aa3b, v15
	v_sub_f32_e32 v16, v89, v16
	v_exp_f32_e32 v15, v15
	v_mul_f32_e32 v16, 0x3fb8aa3b, v16
	v_exp_f32_e32 v16, v16
	v_cvt_pk_bf16_f32 v14, v14, 0
	v_cvt_pk_bf16_f32 v10, v10, 0
	v_lshlrev_b32_e32 v14, 16, v14
	v_and_or_b32 v10, v10, s3, v14
	v_sub_f32_e32 v14, 1.0, v15
	v_mul_f32_e32 v14, v14, v16
	v_sub_f32_e32 v15, v104, v102
	v_add_f32_e32 v16, v104, v90
	v_mul_f32_e32 v15, 0x3fb8aa3b, v15
	v_sub_f32_e32 v16, v46, v16
	v_exp_f32_e32 v15, v15
	v_mul_f32_e32 v16, 0x3fb8aa3b, v16
	v_exp_f32_e32 v16, v16
	v_cvt_pk_bf16_f32 v14, v14, 0
	v_cvt_pk_bf16_f32 v11, v11, 0
	v_lshlrev_b32_e32 v14, 16, v14
	v_and_or_b32 v14, v11, s3, v14
	v_sub_f32_e32 v11, 1.0, v15
	v_mul_f32_e32 v11, v11, v16
	v_sub_f32_e32 v15, v105, v103
	v_add_f32_e32 v16, v105, v91
	v_mul_f32_e32 v15, 0x3fb8aa3b, v15
	v_sub_f32_e32 v16, v47, v16
	v_cvt_pk_bf16_f32 v11, v11, 0
	v_exp_f32_e32 v15, v15
	v_mul_f32_e32 v16, 0x3fb8aa3b, v16
	v_cvt_pk_bf16_f32 v12, v12, 0
	v_exp_f32_e32 v16, v16
	v_lshlrev_b32_e32 v11, 16, v11
	v_and_or_b32 v18, v12, s3, v11
	v_sub_f32_e32 v12, v100, v108
	v_mul_f32_e32 v12, 0x3fb8aa3b, v12
	v_sub_f32_e32 v11, 1.0, v15
	v_exp_f32_e32 v12, v12
	v_mul_f32_e32 v11, v11, v16
	v_cvt_pk_bf16_f32 v11, v11, 0
	v_cvt_pk_bf16_f32 v13, v13, 0
	v_lshlrev_b32_e32 v11, 16, v11
	v_and_or_b32 v22, v13, s3, v11
	v_sub_f32_e32 v11, 1.0, v12
	v_add_f32_e32 v12, v100, v96
	v_sub_f32_e32 v12, v88, v12
	v_sub_f32_e32 v13, v101, v109
	v_add_f32_e32 v15, v101, v97
	v_mul_f32_e32 v12, 0x3fb8aa3b, v12
	v_mul_f32_e32 v13, 0x3fb8aa3b, v13
	v_sub_f32_e32 v15, v89, v15
	v_exp_f32_e32 v12, v12
	v_exp_f32_e32 v13, v13
	v_mul_f32_e32 v15, 0x3fb8aa3b, v15
	v_exp_f32_e32 v15, v15
	v_mul_f32_e32 v11, v11, v12
	v_sub_f32_e32 v12, 1.0, v13
	v_sub_f32_e32 v13, v98, v104
	v_mul_f32_e32 v12, v12, v15
	v_add_f32_e32 v15, v98, v90
	v_mul_f32_e32 v13, 0x3fb8aa3b, v13
	v_sub_f32_e32 v15, v46, v15
	v_sub_f32_e32 v16, v99, v105
	v_exp_f32_e32 v13, v13
	v_mul_f32_e32 v15, 0x3fb8aa3b, v15
	v_mul_f32_e32 v16, 0x3fb8aa3b, v16
	v_exp_f32_e32 v15, v15
	v_exp_f32_e32 v16, v16
	v_sub_f32_e32 v13, 1.0, v13
	v_sub_f32_e32 v17, v94, v100
	v_mul_f32_e32 v13, v13, v15
	v_sub_f32_e32 v15, 1.0, v16
	v_add_f32_e32 v16, v99, v91
	v_sub_f32_e32 v16, v47, v16
	v_mul_f32_e32 v16, 0x3fb8aa3b, v16
	v_add_f32_e32 v19, v94, v96
	v_exp_f32_e32 v16, v16
	v_mul_f32_e32 v17, 0x3fb8aa3b, v17
	v_sub_f32_e32 v19, v88, v19
	v_exp_f32_e32 v17, v17
	v_mul_f32_e32 v19, 0x3fb8aa3b, v19
	v_exp_f32_e32 v19, v19
	v_mul_f32_e32 v15, v15, v16
	v_cvt_pk_bf16_f32 v16, v15, 0
	v_sub_f32_e32 v15, 1.0, v17
	v_mul_f32_e32 v15, v15, v19
	v_sub_f32_e32 v17, v95, v101
	v_add_f32_e32 v19, v95, v97
	v_mul_f32_e32 v17, 0x3fb8aa3b, v17
	v_sub_f32_e32 v19, v89, v19
	v_exp_f32_e32 v17, v17
	v_mul_f32_e32 v19, 0x3fb8aa3b, v19
	v_exp_f32_e32 v19, v19
	v_cvt_pk_bf16_f32 v15, v15, 0
	v_cvt_pk_bf16_f32 v11, v11, 0
	v_lshlrev_b32_e32 v15, 16, v15
	v_and_or_b32 v11, v11, s3, v15
	v_sub_f32_e32 v15, 1.0, v17
	v_mul_f32_e32 v15, v15, v19
	v_sub_f32_e32 v17, v92, v98
	v_add_f32_e32 v19, v92, v90
	v_mul_f32_e32 v17, 0x3fb8aa3b, v17
	v_sub_f32_e32 v19, v46, v19
	v_exp_f32_e32 v17, v17
	v_mul_f32_e32 v19, 0x3fb8aa3b, v19
	v_exp_f32_e32 v19, v19
	v_cvt_pk_bf16_f32 v15, v15, 0
	v_cvt_pk_bf16_f32 v12, v12, 0
	v_lshlrev_b32_e32 v15, 16, v15
	v_and_or_b32 v15, v12, s3, v15
	v_sub_f32_e32 v12, 1.0, v17
	v_mul_f32_e32 v12, v12, v19
	v_sub_f32_e32 v17, v93, v99
	v_add_f32_e32 v19, v93, v91
	v_mul_f32_e32 v17, 0x3fb8aa3b, v17
	v_sub_f32_e32 v19, v47, v19
	v_cvt_pk_bf16_f32 v12, v12, 0
	v_exp_f32_e32 v17, v17
	v_mul_f32_e32 v19, 0x3fb8aa3b, v19
	v_cvt_pk_bf16_f32 v13, v13, 0
	v_exp_f32_e32 v20, v19
	v_lshlrev_b32_e32 v12, 16, v12
	v_and_or_b32 v19, v13, s3, v12
	v_sub_f32_e32 v13, v86, v94
	v_mul_f32_e32 v13, 0x3fb8aa3b, v13
	v_sub_f32_e32 v12, 1.0, v17
	v_exp_f32_e32 v13, v13
	v_mul_f32_e32 v12, v12, v20
	v_cvt_pk_bf16_f32 v12, v12, 0
	v_lshlrev_b32_e32 v12, 16, v12
	v_and_or_b32 v23, v16, s3, v12
	v_sub_f32_e32 v12, 1.0, v13
	v_add_f32_e32 v13, v86, v96
	v_sub_f32_e32 v13, v88, v13
	v_sub_f32_e32 v16, v87, v95
	v_add_f32_e32 v17, v87, v97
	v_mul_f32_e32 v13, 0x3fb8aa3b, v13
	v_mul_f32_e32 v16, 0x3fb8aa3b, v16
	v_sub_f32_e32 v17, v89, v17
	v_exp_f32_e32 v13, v13
	v_exp_f32_e32 v16, v16
	v_mul_f32_e32 v17, 0x3fb8aa3b, v17
	v_exp_f32_e32 v17, v17
; #define GAS __attribute__((address_space(1)))
; #define LAS __attribute__((address_space(3)))
; __device__ __forceinline__ unsigned f2bf(float f) { return pk2(f, 0.f) & 0xffffu; }
; __device__ __forceinline__ void hgrn_passA(Frame& F, u32x2v* HU, float* HD) {
;     ...
;             for (int i = 0; i < 8; ++i)
; #pragma unroll
;                 for (int jj = 0; jj < 4; ++jj) { const int j = 4 * jh + jj; const float kk = 1.f - __expf(i > 0 ? lf[i][jh][jj] - lf[i - 1][jh][jj] : lf[i][jh][jj]);
;                     const float ev = kk * __expf(aend[jh][jj] - (off[jh][jj] + lf[i][jh][jj])); const unsigned bits = f2bf(ev);
;                     if (i & 1) ke[jj][i >> 1] |= bits << 16; else ke[jj][i >> 1] = bits; }
; #pragma unroll
;             for (int jj = 0; jj < 4; ++jj) *(LAS v4u*)(KT + sw512b(8 * c8 + 4 * jh + jj, tq)) = (v4u){ke[jj][0], ke[jj][1], ke[jj][2], ke[jj][3]};
;             __builtin_amdgcn_sched_barrier(0);
;             if (jh == 0) {
; #pragma unroll
;                 for (int i = 0; i < 8; ++i) vq[i] = *(const GAS v4u*)(F.V + rbase + (size_t)i * 512);
	v_mul_f32_e32 v12, v12, v13
	v_sub_f32_e32 v13, 1.0, v16
	v_sub_f32_e32 v16, v36, v92
	v_mul_f32_e32 v13, v13, v17
	v_add_f32_e32 v17, v36, v90
	v_mul_f32_e32 v16, 0x3fb8aa3b, v16
	v_sub_f32_e32 v17, v46, v17
	v_exp_f32_e32 v16, v16
	v_mul_f32_e32 v17, 0x3fb8aa3b, v17
	v_sub_f32_e32 v20, v37, v93
	v_exp_f32_e32 v17, v17
	v_mul_f32_e32 v20, 0x3fb8aa3b, v20
	v_exp_f32_e32 v20, v20
	v_sub_f32_e32 v16, 1.0, v16
	v_mul_f32_e32 v16, v16, v17
	v_cvt_pk_bf16_f32 v17, v16, 0
	v_sub_f32_e32 v16, 1.0, v20
	v_add_f32_e32 v20, v37, v91
	v_sub_f32_e32 v20, v47, v20
	v_mul_f32_e32 v20, 0x3fb8aa3b, v20
	v_sub_f32_e32 v21, v34, v86
	v_exp_f32_e32 v20, v20
	v_mul_f32_e32 v21, 0x3fb8aa3b, v21
	v_exp_f32_e32 v21, v21
	v_add_f32_e32 v24, v34, v96
	v_sub_f32_e32 v24, v88, v24
	v_mul_f32_e32 v24, 0x3fb8aa3b, v24
	v_exp_f32_e32 v24, v24
	v_mul_f32_e32 v16, v16, v20
	v_cvt_pk_bf16_f32 v25, v16, 0
	v_sub_f32_e32 v16, 1.0, v21
	v_sub_f32_e32 v20, v35, v87
	v_add_f32_e32 v21, v35, v97
	v_mul_f32_e32 v20, 0x3fb8aa3b, v20
	v_sub_f32_e32 v21, v89, v21
	v_exp_f32_e32 v20, v20
	v_mul_f32_e32 v21, 0x3fb8aa3b, v21
	v_mul_f32_e32 v16, v16, v24
	v_exp_f32_e32 v21, v21
	v_cvt_pk_bf16_f32 v16, v16, 0
	v_cvt_pk_bf16_f32 v12, v12, 0
	v_lshlrev_b32_e32 v16, 16, v16
	v_and_or_b32 v12, v12, s3, v16
	v_sub_f32_e32 v16, 1.0, v20
	v_sub_f32_e32 v20, v32, v36
	v_mul_f32_e32 v16, v16, v21
	v_mul_f32_e32 v20, 0x3fb8aa3b, v20
	v_add_f32_e32 v21, v32, v90
	v_exp_f32_e32 v20, v20
	v_sub_f32_e32 v21, v46, v21
	v_mul_f32_e32 v21, 0x3fb8aa3b, v21
	v_cvt_pk_bf16_f32 v16, v16, 0
	v_exp_f32_e32 v21, v21
	v_cvt_pk_bf16_f32 v13, v13, 0
	v_lshlrev_b32_e32 v16, 16, v16
	v_and_or_b32 v16, v13, s3, v16
	v_sub_f32_e32 v13, 1.0, v20
	v_sub_f32_e32 v20, v33, v37
	v_mul_f32_e32 v20, 0x3fb8aa3b, v20
	v_mul_f32_e32 v13, v13, v21
	v_exp_f32_e32 v21, v20
	v_add_f32_e32 v20, v33, v91
	v_sub_f32_e32 v20, v47, v20
	v_cvt_pk_bf16_f32 v13, v13, 0
	v_mul_f32_e32 v20, 0x3fb8aa3b, v20
	v_exp_f32_e32 v24, v20
	v_lshlrev_b32_e32 v13, 16, v13
	v_and_or_b32 v20, v17, s3, v13
	v_sub_f32_e32 v17, v30, v34
	v_mul_f32_e32 v17, 0x3fb8aa3b, v17
	v_sub_f32_e32 v13, 1.0, v21
	v_exp_f32_e32 v17, v17
	v_mul_f32_e32 v13, v13, v24
	v_cvt_pk_bf16_f32 v13, v13, 0
	v_lshlrev_b32_e32 v13, 16, v13
	v_and_or_b32 v24, v25, s3, v13
	v_sub_f32_e32 v13, 1.0, v17
	v_add_f32_e32 v17, v30, v96
	v_sub_f32_e32 v30, v6, v30
	v_add_f32_e32 v6, v6, v96
	v_mul_f32_e32 v30, 0x3fb8aa3b, v30
	v_sub_f32_e32 v6, v88, v6
	v_exp_f32_e32 v30, v30
	v_mul_f32_e32 v6, 0x3fb8aa3b, v6
	v_exp_f32_e32 v6, v6
	v_sub_f32_e32 v17, v88, v17
	v_mul_f32_e32 v17, 0x3fb8aa3b, v17
	v_sub_f32_e32 v30, 1.0, v30
	v_exp_f32_e32 v17, v17
	v_mul_f32_e32 v6, v30, v6
	v_sub_f32_e32 v30, v7, v31
	v_add_f32_e32 v7, v7, v97
	v_sub_f32_e32 v21, v31, v35
	v_add_f32_e32 v25, v31, v97
	v_mul_f32_e32 v30, 0x3fb8aa3b, v30
	v_sub_f32_e32 v7, v89, v7
	v_mul_f32_e32 v21, 0x3fb8aa3b, v21
	v_sub_f32_e32 v25, v89, v25
	v_exp_f32_e32 v30, v30
	v_mul_f32_e32 v7, 0x3fb8aa3b, v7
	v_exp_f32_e32 v21, v21
	v_mul_f32_e32 v25, 0x3fb8aa3b, v25
	v_exp_f32_e32 v7, v7
	v_exp_f32_e32 v25, v25
	v_mul_f32_e32 v13, v13, v17
	v_cvt_pk_bf16_f32 v6, v6, 0
	v_cvt_pk_bf16_f32 v13, v13, 0
	v_lshlrev_b32_e32 v6, 16, v6
	v_and_or_b32 v13, v13, s3, v6
	v_sub_f32_e32 v6, 1.0, v30
	v_sub_f32_e32 v17, 1.0, v21
	v_mul_f32_e32 v6, v6, v7
	v_sub_f32_e32 v7, v8, v28
	v_add_f32_e32 v8, v8, v90
	v_mul_f32_e32 v17, v17, v25
	v_sub_f32_e32 v21, v28, v32
	v_add_f32_e32 v25, v28, v90
	v_mul_f32_e32 v7, 0x3fb8aa3b, v7
	v_sub_f32_e32 v8, v46, v8
	v_mul_f32_e32 v21, 0x3fb8aa3b, v21
	v_sub_f32_e32 v25, v46, v25
	v_sub_f32_e32 v32, v29, v33
	v_exp_f32_e32 v7, v7
	v_mul_f32_e32 v8, 0x3fb8aa3b, v8
	v_exp_f32_e32 v21, v21
	v_mul_f32_e32 v25, 0x3fb8aa3b, v25
	v_mul_f32_e32 v32, 0x3fb8aa3b, v32
	v_exp_f32_e32 v8, v8
	v_exp_f32_e32 v25, v25
	v_exp_f32_e32 v32, v32
	v_cvt_pk_bf16_f32 v6, v6, 0
	v_cvt_pk_bf16_f32 v17, v17, 0
	v_lshlrev_b32_e32 v6, 16, v6
	v_and_or_b32 v17, v17, s3, v6
	v_sub_f32_e32 v6, 1.0, v7
	v_sub_f32_e32 v21, 1.0, v21
	v_mul_f32_e32 v6, v6, v8
	v_sub_f32_e32 v7, v9, v29
	v_add_f32_e32 v8, v9, v91
	v_mul_f32_e32 v21, v21, v25
	v_sub_f32_e32 v25, 1.0, v32
	v_add_f32_e32 v32, v29, v91
	v_mul_f32_e32 v7, 0x3fb8aa3b, v7
	v_sub_f32_e32 v8, v47, v8
	v_sub_f32_e32 v32, v47, v32
	v_exp_f32_e32 v7, v7
	v_mul_f32_e32 v8, 0x3fb8aa3b, v8
	v_mul_f32_e32 v32, 0x3fb8aa3b, v32
	v_exp_f32_e32 v8, v8
	v_exp_f32_e32 v32, v32
	v_cvt_pk_bf16_f32 v6, v6, 0
	v_cvt_pk_bf16_f32 v21, v21, 0
	v_lshlrev_b32_e32 v6, 16, v6
	v_and_or_b32 v21, v21, s3, v6
	v_sub_f32_e32 v6, 1.0, v7
	v_mul_f32_e32 v6, v6, v8
	v_mul_f32_e32 v25, v25, v32
	v_cvt_pk_bf16_f32 v6, v6, 0
	v_cvt_pk_bf16_f32 v25, v25, 0
	v_lshlrev_b32_e32 v6, 16, v6
	v_and_or_b32 v25, v25, s3, v6
	ds_write_b128 v56, v[10:13]
	ds_write_b128 v116, v[14:17]
	ds_write_b128 v117, v[18:21]
	ds_write_b128 v118, v[22:25]
	v_lshl_add_u64 v[22:23], v[26:27], 1, s[52:53]
	v_add_f32_e32 v47, v74, v38
	global_load_dwordx4 v[6:9], v[22:23], off
	global_load_dwordx4 v[10:13], v[22:23], off offset:1024
	global_load_dwordx4 v[14:17], v[22:23], off offset:2048
	global_load_dwordx4 v[18:21], v[22:23], off offset:3072
	v_add_co_u32_e64 v34, s[0:1], s2, v22
	v_mul_f32_e32 v22, 0x3fb8aa3b, v38
	v_sub_f32_e32 v47, v70, v47
	v_add_f32_e32 v87, v75, v39
	v_exp_f32_e32 v46, v22
	v_mul_f32_e32 v47, 0x3fb8aa3b, v47
	v_mul_f32_e32 v86, 0x3fb8aa3b, v39
	v_sub_f32_e32 v87, v71, v87
	v_exp_f32_e32 v47, v47
	v_exp_f32_e32 v86, v86
	v_mul_f32_e32 v87, 0x3fb8aa3b, v87
	v_exp_f32_e32 v87, v87
	v_sub_f32_e32 v46, 1.0, v46
	v_mul_f32_e32 v46, v46, v47
	v_sub_f32_e32 v47, 1.0, v86
	v_mul_f32_e32 v47, v47, v87
	v_add_f32_e32 v87, v72, v42
; #define GAS __attribute__((address_space(1)))
; #define LAS __attribute__((address_space(3)))
; __device__ __forceinline__ unsigned f2bf(float f) { return pk2(f, 0.f) & 0xffffu; }
; __device__ __forceinline__ void hgrn_passA(Frame& F, u32x2v* HU, float* HD) {
;     ...
;             for (int i = 0; i < 8; ++i)
; #pragma unroll
;                 for (int jj = 0; jj < 4; ++jj) { const int j = 4 * jh + jj; const float kk = 1.f - __expf(i > 0 ? lf[i][jh][jj] - lf[i - 1][jh][jj] : lf[i][jh][jj]);
;                     const float ev = kk * __expf(aend[jh][jj] - (off[jh][jj] + lf[i][jh][jj])); const unsigned bits = f2bf(ev);
;                     if (i & 1) ke[jj][i >> 1] |= bits << 16; else ke[jj][i >> 1] = bits; }
; #pragma unroll
;             for (int jj = 0; jj < 4; ++jj) *(LAS v4u*)(KT + sw512b(8 * c8 + 4 * jh + jj, tq)) = (v4u){ke[jj][0], ke[jj][1], ke[jj][2], ke[jj][3]};
;             __builtin_amdgcn_sched_barrier(0);
;             if (jh == 0) {
; #pragma unroll
;                 for (int i = 0; i < 8; ++i) vq[i] = *(const GAS v4u*)(F.V + rbase + (size_t)i * 512);
	v_mul_f32_e32 v86, 0x3fb8aa3b, v42
	v_sub_f32_e32 v87, v68, v87
	v_exp_f32_e32 v86, v86
	v_mul_f32_e32 v87, 0x3fb8aa3b, v87
	v_mul_f32_e32 v88, 0x3fb8aa3b, v43
	v_exp_f32_e32 v87, v87
	v_exp_f32_e32 v88, v88
	v_sub_f32_e32 v86, 1.0, v86
	v_sub_f32_e32 v38, v50, v38
	v_mul_f32_e32 v86, v86, v87
	v_sub_f32_e32 v87, 1.0, v88
	v_add_f32_e32 v88, v73, v43
	v_sub_f32_e32 v88, v69, v88
	v_add_f32_e32 v89, v50, v74
	v_mul_f32_e32 v88, 0x3fb8aa3b, v88
	v_mul_f32_e32 v38, 0x3fb8aa3b, v38
	v_sub_f32_e32 v89, v70, v89
	v_exp_f32_e32 v88, v88
	v_exp_f32_e32 v38, v38
	v_mul_f32_e32 v89, 0x3fb8aa3b, v89
	v_exp_f32_e32 v89, v89
	v_mul_f32_e32 v87, v87, v88
	v_sub_f32_e32 v38, 1.0, v38
	v_sub_f32_e32 v39, v51, v39
	v_add_f32_e32 v88, v51, v75
	v_mul_f32_e32 v38, v38, v89
	v_mul_f32_e32 v39, 0x3fb8aa3b, v39
	v_sub_f32_e32 v88, v71, v88
	v_cvt_pk_bf16_f32 v38, v38, 0
	v_exp_f32_e32 v39, v39
	v_mul_f32_e32 v88, 0x3fb8aa3b, v88
	v_sub_f32_e32 v42, v84, v42
	v_cvt_pk_bf16_f32 v46, v46, 0
	v_exp_f32_e32 v88, v88
	v_lshlrev_b32_e32 v38, 16, v38
	v_mul_f32_e32 v42, 0x3fb8aa3b, v42
	v_and_or_b32 v38, v46, s3, v38
	v_exp_f32_e32 v46, v42
	v_add_f32_e32 v42, v84, v72
	v_sub_f32_e32 v42, v68, v42
	v_sub_f32_e32 v39, 1.0, v39
	v_mul_f32_e32 v42, 0x3fb8aa3b, v42
	v_mul_f32_e32 v39, v39, v88
	v_exp_f32_e32 v88, v42
	v_cvt_pk_bf16_f32 v39, v39, 0
	v_sub_f32_e32 v43, v85, v43
	v_cvt_pk_bf16_f32 v47, v47, 0
	v_lshlrev_b32_e32 v39, 16, v39
	v_mul_f32_e32 v43, 0x3fb8aa3b, v43
	v_and_or_b32 v42, v47, s3, v39
	v_sub_f32_e32 v39, 1.0, v46
	v_exp_f32_e32 v43, v43
	v_add_f32_e32 v46, v85, v73
	v_mul_f32_e32 v39, v39, v88
	v_sub_f32_e32 v46, v69, v46
	v_cvt_pk_bf16_f32 v39, v39, 0
	v_mul_f32_e32 v46, 0x3fb8aa3b, v46
	v_cvt_pk_bf16_f32 v86, v86, 0
	v_exp_f32_e32 v47, v46
	v_lshlrev_b32_e32 v39, 16, v39
	v_and_or_b32 v46, v86, s3, v39
	v_sub_f32_e32 v39, 1.0, v43
	v_sub_f32_e32 v43, v82, v50
	v_mul_f32_e32 v43, 0x3fb8aa3b, v43
	v_exp_f32_e32 v43, v43
	v_mul_f32_e32 v39, v39, v47
	v_cvt_pk_bf16_f32 v39, v39, 0
	v_cvt_pk_bf16_f32 v87, v87, 0
	v_lshlrev_b32_e32 v39, 16, v39
	v_and_or_b32 v50, v87, s3, v39
	v_sub_f32_e32 v39, 1.0, v43
	v_add_f32_e32 v43, v82, v74
	v_sub_f32_e32 v43, v70, v43
	v_sub_f32_e32 v47, v83, v51
	v_add_f32_e32 v51, v83, v75
	v_mul_f32_e32 v43, 0x3fb8aa3b, v43
	v_mul_f32_e32 v47, 0x3fb8aa3b, v47
	v_sub_f32_e32 v51, v71, v51
	v_exp_f32_e32 v43, v43
	v_exp_f32_e32 v47, v47
	v_mul_f32_e32 v51, 0x3fb8aa3b, v51
	v_exp_f32_e32 v51, v51
	v_mul_f32_e32 v39, v39, v43
	v_sub_f32_e32 v43, 1.0, v47
	v_sub_f32_e32 v47, v78, v84
	v_mul_f32_e32 v43, v43, v51
	v_add_f32_e32 v51, v78, v72
	v_mul_f32_e32 v47, 0x3fb8aa3b, v47
	v_sub_f32_e32 v51, v68, v51
	v_sub_f32_e32 v84, v79, v85
	v_exp_f32_e32 v47, v47
	v_mul_f32_e32 v51, 0x3fb8aa3b, v51
	v_mul_f32_e32 v84, 0x3fb8aa3b, v84
	v_exp_f32_e32 v51, v51
	v_exp_f32_e32 v84, v84
	v_sub_f32_e32 v47, 1.0, v47
	v_sub_f32_e32 v82, v76, v82
	v_mul_f32_e32 v47, v47, v51
	v_sub_f32_e32 v51, 1.0, v84
	v_add_f32_e32 v84, v79, v73
	v_sub_f32_e32 v84, v69, v84
	v_mul_f32_e32 v84, 0x3fb8aa3b, v84
	v_exp_f32_e32 v84, v84
	v_add_f32_e32 v85, v76, v74
	v_mul_f32_e32 v82, 0x3fb8aa3b, v82
	v_sub_f32_e32 v85, v70, v85
	v_exp_f32_e32 v82, v82
	v_mul_f32_e32 v85, 0x3fb8aa3b, v85
	v_exp_f32_e32 v85, v85
	v_mul_f32_e32 v51, v51, v84
	v_sub_f32_e32 v83, v77, v83
	v_add_f32_e32 v84, v77, v75
	v_mul_f32_e32 v83, 0x3fb8aa3b, v83
	v_sub_f32_e32 v84, v71, v84
	v_sub_f32_e32 v82, 1.0, v82
	v_exp_f32_e32 v83, v83
	v_mul_f32_e32 v84, 0x3fb8aa3b, v84
	v_mul_f32_e32 v82, v82, v85
	v_exp_f32_e32 v84, v84
	v_cvt_pk_bf16_f32 v82, v82, 0
	v_cvt_pk_bf16_f32 v39, v39, 0
	v_lshlrev_b32_e32 v82, 16, v82
	v_and_or_b32 v39, v39, s3, v82
	v_sub_f32_e32 v82, 1.0, v83
	v_sub_f32_e32 v78, v48, v78
	v_add_f32_e32 v83, v48, v72
	v_mul_f32_e32 v82, v82, v84
	v_mul_f32_e32 v78, 0x3fb8aa3b, v78
	v_sub_f32_e32 v83, v68, v83
	v_cvt_pk_bf16_f32 v82, v82, 0
	v_exp_f32_e32 v78, v78
	v_mul_f32_e32 v83, 0x3fb8aa3b, v83
	v_addc_co_u32_e64 v35, s[0:1], 0, v23, s[0:1]
	v_cvt_pk_bf16_f32 v43, v43, 0
	v_exp_f32_e32 v83, v83
	v_lshlrev_b32_e32 v82, 16, v82
	global_load_dwordx4 v[22:25], v[34:35], off
	global_load_dwordx4 v[26:29], v[34:35], off offset:1024
	global_load_dwordx4 v[30:33], v[34:35], off offset:2048
	s_nop 0
	global_load_dwordx4 v[34:37], v[34:35], off offset:3072
	v_and_or_b32 v43, v43, s3, v82
	v_sub_f32_e32 v79, v49, v79
	v_add_f32_e32 v82, v49, v73
	v_mul_f32_e32 v79, 0x3fb8aa3b, v79
	v_sub_f32_e32 v82, v69, v82
	v_sub_f32_e32 v78, 1.0, v78
	v_exp_f32_e32 v79, v79
	v_mul_f32_e32 v82, 0x3fb8aa3b, v82
	v_mul_f32_e32 v78, v78, v83
	v_exp_f32_e32 v82, v82
	v_cvt_pk_bf16_f32 v78, v78, 0
	v_cvt_pk_bf16_f32 v47, v47, 0
	v_lshlrev_b32_e32 v78, 16, v78
	v_and_or_b32 v47, v47, s3, v78
	v_sub_f32_e32 v78, 1.0, v79
	v_mul_f32_e32 v78, v78, v82
	v_cvt_pk_bf16_f32 v78, v78, 0
	v_cvt_pk_bf16_f32 v51, v51, 0
	v_lshlrev_b32_e32 v78, 16, v78
	v_sub_f32_e32 v76, v40, v76
	v_and_or_b32 v51, v51, s3, v78
	v_add_f32_e32 v78, v40, v74
	v_mul_f32_e32 v76, 0x3fb8aa3b, v76
	v_sub_f32_e32 v78, v70, v78
	v_exp_f32_e32 v76, v76
	v_mul_f32_e32 v78, 0x3fb8aa3b, v78
	v_exp_f32_e32 v78, v78
	v_sub_f32_e32 v48, v44, v48
	v_sub_f32_e32 v76, 1.0, v76
	v_sub_f32_e32 v77, v41, v77
	v_mul_f32_e32 v76, v76, v78
	v_add_f32_e32 v78, v44, v72
	v_add_f32_e32 v79, v41, v75
	v_mul_f32_e32 v48, 0x3fb8aa3b, v48
	v_sub_f32_e32 v78, v68, v78
	v_mul_f32_e32 v77, 0x3fb8aa3b, v77
	v_sub_f32_e32 v79, v71, v79
	v_exp_f32_e32 v48, v48
	v_mul_f32_e32 v78, 0x3fb8aa3b, v78
	v_exp_f32_e32 v77, v77
	v_mul_f32_e32 v79, 0x3fb8aa3b, v79
	v_exp_f32_e32 v78, v78
	v_exp_f32_e32 v79, v79
	v_sub_f32_e32 v48, 1.0, v48
	v_sub_f32_e32 v77, 1.0, v77
; #define GAS __attribute__((address_space(1)))
; #define LAS __attribute__((address_space(3)))
; __device__ __forceinline__ unsigned f2bf(float f) { return pk2(f, 0.f) & 0xffffu; }
; __device__ __forceinline__ void hgrn_passA(Frame& F, u32x2v* HU, float* HD) {
;     ...
;             for (int i = 0; i < 8; ++i)
; #pragma unroll
;                 for (int jj = 0; jj < 4; ++jj) { const int j = 4 * jh + jj; const float kk = 1.f - __expf(i > 0 ? lf[i][jh][jj] - lf[i - 1][jh][jj] : lf[i][jh][jj]);
;                     const float ev = kk * __expf(aend[jh][jj] - (off[jh][jj] + lf[i][jh][jj])); const unsigned bits = f2bf(ev);
;                     if (i & 1) ke[jj][i >> 1] |= bits << 16; else ke[jj][i >> 1] = bits; }
; #pragma unroll
;             for (int jj = 0; jj < 4; ++jj) *(LAS v4u*)(KT + sw512b(8 * c8 + 4 * jh + jj, tq)) = (v4u){ke[jj][0], ke[jj][1], ke[jj][2], ke[jj][3]};
;             __builtin_amdgcn_sched_barrier(0);
;             if (jh == 0) {
; #pragma unroll
;                 for (int i = 0; i < 8; ++i) vq[i] = *(const GAS v4u*)(F.V + rbase + (size_t)i * 512);
;             }
;         }
; #pragma unroll
;         for (int j = 0; j < 8; ++j) {
;             unsigned vv[4];
; #pragma unroll
;             for (int p = 0; p < 4; ++p) { const unsigned lo = (j & 1) ? (vq[2 * p][j >> 1] >> 16) : (vq[2 * p][j >> 1] & 0xffffu), hi = (j & 1) ? (vq[2 * p + 1][j >> 1] & 0xffff0000u) : (vq[2 * p + 1][j >> 1] << 16); vv[p] = lo | hi; }
;             *(LAS v4u*)(VT + sw512b(8 * c8 + j, tq)) = (v4u){vv[0], vv[1], vv[2], vv[3]}; }
	v_sub_f32_e32 v49, v45, v49
	v_mul_f32_e32 v48, v48, v78
	v_add_f32_e32 v78, v45, v73
	v_mul_f32_e32 v77, v77, v79
	v_mul_f32_e32 v49, 0x3fb8aa3b, v49
	v_sub_f32_e32 v78, v69, v78
	v_sub_f32_e32 v40, v52, v40
	v_add_f32_e32 v79, v52, v74
	v_exp_f32_e32 v49, v49
	v_mul_f32_e32 v78, 0x3fb8aa3b, v78
	v_mul_f32_e32 v40, 0x3fb8aa3b, v40
	v_sub_f32_e32 v79, v70, v79
	v_exp_f32_e32 v78, v78
	v_exp_f32_e32 v40, v40
	v_mul_f32_e32 v79, 0x3fb8aa3b, v79
	v_exp_f32_e32 v79, v79
	v_sub_f32_e32 v49, 1.0, v49
	v_mul_f32_e32 v49, v49, v78
	v_sub_f32_e32 v40, 1.0, v40
	v_sub_f32_e32 v41, v53, v41
	v_add_f32_e32 v78, v53, v75
	v_mul_f32_e32 v40, v40, v79
	v_mul_f32_e32 v41, 0x3fb8aa3b, v41
	v_sub_f32_e32 v78, v71, v78
	v_cvt_pk_bf16_f32 v40, v40, 0
	v_exp_f32_e32 v41, v41
	v_mul_f32_e32 v78, 0x3fb8aa3b, v78
	v_sub_f32_e32 v44, v66, v44
	v_cvt_pk_bf16_f32 v76, v76, 0
	v_exp_f32_e32 v78, v78
	v_lshlrev_b32_e32 v40, 16, v40
	v_mul_f32_e32 v44, 0x3fb8aa3b, v44
	v_and_or_b32 v40, v76, s3, v40
	v_exp_f32_e32 v76, v44
	v_add_f32_e32 v44, v66, v72
	v_sub_f32_e32 v44, v68, v44
	v_sub_f32_e32 v41, 1.0, v41
	v_mul_f32_e32 v44, 0x3fb8aa3b, v44
	v_mul_f32_e32 v41, v41, v78
	v_exp_f32_e32 v78, v44
	v_cvt_pk_bf16_f32 v41, v41, 0
	v_sub_f32_e32 v45, v67, v45
	v_cvt_pk_bf16_f32 v77, v77, 0
	v_lshlrev_b32_e32 v41, 16, v41
	v_mul_f32_e32 v45, 0x3fb8aa3b, v45
	v_and_or_b32 v44, v77, s3, v41
	v_sub_f32_e32 v41, 1.0, v76
	v_exp_f32_e32 v45, v45
	v_add_f32_e32 v76, v67, v73
	v_mul_f32_e32 v41, v41, v78
	v_sub_f32_e32 v76, v69, v76
	v_cvt_pk_bf16_f32 v41, v41, 0
	v_mul_f32_e32 v76, 0x3fb8aa3b, v76
	v_cvt_pk_bf16_f32 v48, v48, 0
	v_exp_f32_e32 v76, v76
	v_lshlrev_b32_e32 v41, 16, v41
	v_and_or_b32 v48, v48, s3, v41
	v_sub_f32_e32 v41, 1.0, v45
	v_sub_f32_e32 v45, v64, v52
	v_mul_f32_e32 v45, 0x3fb8aa3b, v45
	v_exp_f32_e32 v45, v45
	v_mul_f32_e32 v41, v41, v76
	v_cvt_pk_bf16_f32 v41, v41, 0
	v_cvt_pk_bf16_f32 v49, v49, 0
	v_lshlrev_b32_e32 v41, 16, v41
	v_and_or_b32 v52, v49, s3, v41
	v_sub_f32_e32 v41, 1.0, v45
	v_add_f32_e32 v45, v64, v74
	v_sub_f32_e32 v64, v2, v64
	v_add_f32_e32 v2, v2, v74
	v_mul_f32_e32 v64, 0x3fb8aa3b, v64
	v_sub_f32_e32 v2, v70, v2
	v_exp_f32_e32 v64, v64
	v_mul_f32_e32 v2, 0x3fb8aa3b, v2
	v_exp_f32_e32 v2, v2
	v_sub_f32_e32 v45, v70, v45
	v_mul_f32_e32 v45, 0x3fb8aa3b, v45
	v_sub_f32_e32 v64, 1.0, v64
	v_exp_f32_e32 v45, v45
	v_mul_f32_e32 v2, v64, v2
	v_sub_f32_e32 v64, v3, v65
	v_add_f32_e32 v3, v3, v75
	v_sub_f32_e32 v49, v65, v53
	v_add_f32_e32 v53, v65, v75
	v_mul_f32_e32 v64, 0x3fb8aa3b, v64
	v_sub_f32_e32 v3, v71, v3
	v_mul_f32_e32 v49, 0x3fb8aa3b, v49
	v_sub_f32_e32 v53, v71, v53
	v_exp_f32_e32 v64, v64
	v_mul_f32_e32 v3, 0x3fb8aa3b, v3
	v_exp_f32_e32 v49, v49
	v_mul_f32_e32 v53, 0x3fb8aa3b, v53
	v_exp_f32_e32 v3, v3
	v_exp_f32_e32 v53, v53
	v_mul_f32_e32 v41, v41, v45
	v_cvt_pk_bf16_f32 v2, v2, 0
	v_cvt_pk_bf16_f32 v41, v41, 0
	v_lshlrev_b32_e32 v2, 16, v2
	v_and_or_b32 v41, v41, s3, v2
	v_sub_f32_e32 v2, 1.0, v64
	v_sub_f32_e32 v45, 1.0, v49
	v_mul_f32_e32 v2, v2, v3
	v_sub_f32_e32 v3, v4, v62
	v_add_f32_e32 v4, v4, v72
	v_mul_f32_e32 v45, v45, v53
	v_sub_f32_e32 v49, v62, v66
	v_add_f32_e32 v53, v62, v72
	v_mul_f32_e32 v3, 0x3fb8aa3b, v3
	v_sub_f32_e32 v4, v68, v4
	v_mul_f32_e32 v49, 0x3fb8aa3b, v49
	v_sub_f32_e32 v53, v68, v53
	v_sub_f32_e32 v66, v63, v67
	v_exp_f32_e32 v3, v3
	v_mul_f32_e32 v4, 0x3fb8aa3b, v4
	v_exp_f32_e32 v49, v49
	v_mul_f32_e32 v53, 0x3fb8aa3b, v53
	v_mul_f32_e32 v66, 0x3fb8aa3b, v66
	v_exp_f32_e32 v4, v4
	v_exp_f32_e32 v53, v53
	v_exp_f32_e32 v66, v66
	v_cvt_pk_bf16_f32 v2, v2, 0
	v_cvt_pk_bf16_f32 v45, v45, 0
	v_lshlrev_b32_e32 v2, 16, v2
	v_and_or_b32 v45, v45, s3, v2
	v_sub_f32_e32 v2, 1.0, v3
	v_sub_f32_e32 v49, 1.0, v49
	v_mul_f32_e32 v2, v2, v4
	v_sub_f32_e32 v3, v5, v63
	v_add_f32_e32 v4, v5, v73
	v_mul_f32_e32 v49, v49, v53
	v_sub_f32_e32 v53, 1.0, v66
	v_add_f32_e32 v66, v63, v73
	v_mul_f32_e32 v3, 0x3fb8aa3b, v3
	v_sub_f32_e32 v4, v69, v4
	v_sub_f32_e32 v66, v69, v66
	v_exp_f32_e32 v3, v3
	v_mul_f32_e32 v4, 0x3fb8aa3b, v4
	v_mul_f32_e32 v66, 0x3fb8aa3b, v66
	v_exp_f32_e32 v4, v4
	v_exp_f32_e32 v66, v66
	v_cvt_pk_bf16_f32 v2, v2, 0
	v_cvt_pk_bf16_f32 v49, v49, 0
	v_lshlrev_b32_e32 v2, 16, v2
	v_and_or_b32 v49, v49, s3, v2
	v_sub_f32_e32 v2, 1.0, v3
	v_mul_f32_e32 v2, v2, v4
	v_mul_f32_e32 v53, v53, v66
	v_cvt_pk_bf16_f32 v2, v2, 0
	v_cvt_pk_bf16_f32 v53, v53, 0
	v_lshlrev_b32_e32 v2, 16, v2
	v_and_or_b32 v53, v53, s3, v2
	ds_write_b128 v119, v[38:41]
	ds_write_b128 v120, v[42:45]
	ds_write_b128 v121, v[46:49]
	ds_write_b128 v122, v[50:53]
	s_waitcnt vmcnt(7)
	v_and_b32_e32 v2, 0xffff, v6
	s_waitcnt vmcnt(5)
	v_and_b32_e32 v3, 0xffff, v14
	s_waitcnt vmcnt(3)
	v_and_b32_e32 v4, 0xffff, v22
	s_waitcnt vmcnt(1)
	v_and_b32_e32 v5, 0xffff, v30
	v_lshl_or_b32 v2, v10, 16, v2
	v_lshl_or_b32 v3, v18, 16, v3
	v_lshl_or_b32 v4, v26, 16, v4
	s_waitcnt vmcnt(0)
	v_lshl_or_b32 v5, v34, 16, v5
	ds_write_b128 v123, v[2:5]
	v_lshrrev_b32_e32 v2, 16, v6
	v_lshrrev_b32_e32 v3, 16, v14
	v_lshrrev_b32_e32 v4, 16, v22
	v_lshrrev_b32_e32 v5, 16, v30
	v_and_or_b32 v2, v10, s8, v2
	v_and_or_b32 v3, v18, s8, v3
	v_and_or_b32 v4, v26, s8, v4
	v_and_or_b32 v5, v34, s8, v5
	ds_write_b128 v124, v[2:5]
	v_and_b32_e32 v2, 0xffff, v7
	v_and_b32_e32 v3, 0xffff, v15
	v_and_b32_e32 v4, 0xffff, v23
	v_and_b32_e32 v5, 0xffff, v31
	v_lshl_or_b32 v2, v11, 16, v2
	v_lshl_or_b32 v3, v19, 16, v3
	v_lshl_or_b32 v4, v27, 16, v4
	v_lshl_or_b32 v5, v35, 16, v5
	ds_write_b128 v125, v[2:5]
	v_lshrrev_b32_e32 v2, 16, v7
	v_lshrrev_b32_e32 v3, 16, v15
	v_lshrrev_b32_e32 v4, 16, v23
	v_lshrrev_b32_e32 v5, 16, v31
	v_and_or_b32 v2, v11, s8, v2
	v_and_or_b32 v3, v19, s8, v3
	v_and_or_b32 v4, v27, s8, v4
	v_and_or_b32 v5, v35, s8, v5
	ds_write_b128 v126, v[2:5]
	v_and_b32_e32 v2, 0xffff, v8
	v_and_b32_e32 v3, 0xffff, v16
	v_and_b32_e32 v4, 0xffff, v24
	v_and_b32_e32 v5, 0xffff, v32
	v_lshl_or_b32 v2, v12, 16, v2
	v_lshl_or_b32 v3, v20, 16, v3
	v_lshl_or_b32 v4, v28, 16, v4
	v_lshl_or_b32 v5, v36, 16, v5
	ds_write_b128 v127, v[2:5]
	v_lshrrev_b32_e32 v2, 16, v8
	v_lshrrev_b32_e32 v3, 16, v16
	v_lshrrev_b32_e32 v4, 16, v24
	v_lshrrev_b32_e32 v5, 16, v32
	v_and_or_b32 v2, v12, s8, v2
	v_and_or_b32 v3, v20, s8, v3
	v_and_or_b32 v4, v28, s8, v4
	v_and_or_b32 v5, v36, s8, v5
	ds_write_b128 v128, v[2:5]
	v_and_b32_e32 v2, 0xffff, v9
	v_and_b32_e32 v3, 0xffff, v17
	v_and_b32_e32 v4, 0xffff, v25
	v_and_b32_e32 v5, 0xffff, v33
	v_lshl_or_b32 v2, v13, 16, v2
	v_lshl_or_b32 v3, v21, 16, v3
	v_lshl_or_b32 v4, v29, 16, v4
	v_lshl_or_b32 v5, v37, 16, v5
	ds_write_b128 v129, v[2:5]
	v_lshrrev_b32_e32 v2, 16, v9
	v_lshrrev_b32_e32 v3, 16, v17
	v_lshrrev_b32_e32 v4, 16, v25
	v_lshrrev_b32_e32 v5, 16, v33
	v_and_or_b32 v2, v13, s8, v2
	v_and_or_b32 v3, v21, s8, v3
	v_and_or_b32 v4, v29, s8, v4
	v_and_or_b32 v5, v37, s8, v5
	ds_write_b128 v130, v[2:5]
	s_waitcnt lgkmcnt(0)
	s_barrier
; __device__ __forceinline__ f32x4 mma16(bf16x8 a, bf16x8 b, f32x4 c) { return __builtin_amdgcn_mfma_f32_16x16x32_bf16(a, b, c, 0, 0, 0); }
; __device__ __forceinline__ void hgrn_passA(Frame& F, u32x2v* HU, float* HD) {
;     ...
;         f32x4 acc[8];
; #pragma unroll
;         for (int n = 0; n < 8; ++n) acc[n] = (f32x4){0.f, 0.f, 0.f, 0.f};
; #pragma unroll
;         for (int ks = 0; ks < 8; ++ks) {
;             const bf16x8 af = ldfrag(KT + sw512b(16 * w + l15, 4 * ks + lq));
; #pragma unroll
;             for (int n = 0; n < 8; ++n) acc[n] = mma16(af, ldfrag(VT + sw512b(16 * n + l15, 4 * ks + lq)), acc[n]);
;         }
	ds_read_b128 v[2:5], v131
	ds_read_b128 v[6:9], v132
	ds_read_b128 v[10:13], v133
	ds_read_b128 v[14:17], v134
	ds_read_b128 v[18:21], v135
	ds_read_b128 v[22:25], v136
	ds_read_b128 v[26:29], v137
	ds_read_b128 v[30:33], v138
	ds_read_b128 v[34:37], v139
	ds_read_b128 v[38:41], v140
	s_waitcnt lgkmcnt(8)
	v_mfma_f32_16x16x32_bf16 v[6:9], v[2:5], v[6:9], 0
	s_add_i32 s4, s4, s79
	s_cmpk_lt_i32 s4, 0x100
	s_waitcnt lgkmcnt(7)
	v_mfma_f32_16x16x32_bf16 v[10:13], v[2:5], v[10:13], 0
	s_waitcnt lgkmcnt(6)
	v_mfma_f32_16x16x32_bf16 v[14:17], v[2:5], v[14:17], 0
	s_waitcnt lgkmcnt(5)
	v_mfma_f32_16x16x32_bf16 v[18:21], v[2:5], v[18:21], 0
	s_waitcnt lgkmcnt(4)
	v_mfma_f32_16x16x32_bf16 v[22:25], v[2:5], v[22:25], 0
	s_waitcnt lgkmcnt(3)
	v_mfma_f32_16x16x32_bf16 v[26:29], v[2:5], v[26:29], 0
	s_waitcnt lgkmcnt(2)
	v_mfma_f32_16x16x32_bf16 v[30:33], v[2:5], v[30:33], 0
	s_waitcnt lgkmcnt(1)
	v_mfma_f32_16x16x32_bf16 v[2:5], v[2:5], v[34:37], 0
	ds_read_b128 v[34:37], v141
	ds_read_b128 v[42:45], v142
	s_waitcnt lgkmcnt(1)
	v_mfma_f32_16x16x32_bf16 v[6:9], v[38:41], v[34:37], v[6:9]
	s_waitcnt lgkmcnt(0)
	v_mfma_f32_16x16x32_bf16 v[10:13], v[38:41], v[42:45], v[10:13]
	ds_read_b128 v[34:37], v143
	ds_read_b128 v[42:45], v144
	s_waitcnt lgkmcnt(1)
	v_mfma_f32_16x16x32_bf16 v[14:17], v[38:41], v[34:37], v[14:17]
	s_waitcnt lgkmcnt(0)
	v_mfma_f32_16x16x32_bf16 v[18:21], v[38:41], v[42:45], v[18:21]
	ds_read_b128 v[34:37], v145
	ds_read_b128 v[42:45], v146
	s_waitcnt lgkmcnt(1)
	v_mfma_f32_16x16x32_bf16 v[22:25], v[38:41], v[34:37], v[22:25]
	s_waitcnt lgkmcnt(0)
	v_mfma_f32_16x16x32_bf16 v[26:29], v[38:41], v[42:45], v[26:29]
	ds_read_b128 v[34:37], v147
	ds_read_b128 v[42:45], v148
	s_waitcnt lgkmcnt(1)
	v_mfma_f32_16x16x32_bf16 v[30:33], v[38:41], v[34:37], v[30:33]
	ds_read_b128 v[34:37], v149
	s_waitcnt lgkmcnt(1)
	v_mfma_f32_16x16x32_bf16 v[2:5], v[38:41], v[42:45], v[2:5]
	ds_read_b128 v[38:41], v150
	s_waitcnt lgkmcnt(0)
	v_mfma_f32_16x16x32_bf16 v[6:9], v[34:37], v[38:41], v[6:9]
	ds_read_b128 v[38:41], v151
	ds_read_b128 v[42:45], v152
	s_waitcnt lgkmcnt(1)
	v_mfma_f32_16x16x32_bf16 v[10:13], v[34:37], v[38:41], v[10:13]
	s_waitcnt lgkmcnt(0)
	v_mfma_f32_16x16x32_bf16 v[14:17], v[34:37], v[42:45], v[14:17]
	ds_read_b128 v[38:41], v153
	ds_read_b128 v[42:45], v154
	s_waitcnt lgkmcnt(1)
	v_mfma_f32_16x16x32_bf16 v[18:21], v[34:37], v[38:41], v[18:21]
	s_waitcnt lgkmcnt(0)
	v_mfma_f32_16x16x32_bf16 v[22:25], v[34:37], v[42:45], v[22:25]
	ds_read_b128 v[38:41], v155
	ds_read_b128 v[42:45], v156
	s_waitcnt lgkmcnt(1)
	v_mfma_f32_16x16x32_bf16 v[26:29], v[34:37], v[38:41], v[26:29]
	ds_read_b128 v[38:41], v157
	s_waitcnt lgkmcnt(1)
	v_mfma_f32_16x16x32_bf16 v[30:33], v[34:37], v[42:45], v[30:33]
	ds_read_b128 v[42:45], v158
	s_waitcnt lgkmcnt(1)
	v_mfma_f32_16x16x32_bf16 v[2:5], v[34:37], v[38:41], v[2:5]
	ds_read_b128 v[34:37], v159
	ds_read_b128 v[38:41], v160
	s_waitcnt lgkmcnt(1)
	v_mfma_f32_16x16x32_bf16 v[6:9], v[42:45], v[34:37], v[6:9]
	s_waitcnt lgkmcnt(0)
	v_mfma_f32_16x16x32_bf16 v[10:13], v[42:45], v[38:41], v[10:13]
	ds_read_b128 v[34:37], v161
	ds_read_b128 v[38:41], v162
	s_waitcnt lgkmcnt(1)
	v_mfma_f32_16x16x32_bf16 v[14:17], v[42:45], v[34:37], v[14:17]
	s_waitcnt lgkmcnt(0)
	v_mfma_f32_16x16x32_bf16 v[18:21], v[42:45], v[38:41], v[18:21]
	ds_read_b128 v[34:37], v163
	ds_read_b128 v[38:41], v164
	s_waitcnt lgkmcnt(1)
	v_mfma_f32_16x16x32_bf16 v[22:25], v[42:45], v[34:37], v[22:25]
	s_waitcnt lgkmcnt(0)
	v_mfma_f32_16x16x32_bf16 v[26:29], v[42:45], v[38:41], v[26:29]
	ds_read_b128 v[34:37], v165
	ds_read_b128 v[38:41], v166
	s_waitcnt lgkmcnt(1)
	v_mfma_f32_16x16x32_bf16 v[30:33], v[42:45], v[34:37], v[30:33]
	ds_read_b128 v[34:37], v167
	s_waitcnt lgkmcnt(1)
	v_mfma_f32_16x16x32_bf16 v[2:5], v[42:45], v[38:41], v[2:5]
	ds_read_b128 v[38:41], v168
	s_waitcnt lgkmcnt(0)
	v_mfma_f32_16x16x32_bf16 v[6:9], v[34:37], v[38:41], v[6:9]
	ds_read_b128 v[38:41], v169
	ds_read_b128 v[42:45], v170
	s_waitcnt lgkmcnt(1)
	v_mfma_f32_16x16x32_bf16 v[10:13], v[34:37], v[38:41], v[10:13]
	s_waitcnt lgkmcnt(0)
	v_mfma_f32_16x16x32_bf16 v[14:17], v[34:37], v[42:45], v[14:17]
	ds_read_b128 v[38:41], v171
	ds_read_b128 v[42:45], v172
	s_waitcnt lgkmcnt(1)
; __device__ __forceinline__ unsigned pk2(float lo, float hi) { const pkf2_t v = {lo, hi}; const pkb2_t b = __builtin_convertvector(v, pkb2_t); return __builtin_bit_cast(unsigned, b); }
; __device__ __forceinline__ f32x4 mma16(bf16x8 a, bf16x8 b, f32x4 c) { return __builtin_amdgcn_mfma_f32_16x16x32_bf16(a, b, c, 0, 0, 0); }
; __device__ __forceinline__ void hgrn_passA(Frame& F, u32x2v* HU, float* HD) {
;     ...
;         for (int ks = 0; ks < 8; ++ks) {
;             const bf16x8 af = ldfrag(KT + sw512b(16 * w + l15, 4 * ks + lq));
; #pragma unroll
;             for (int n = 0; n < 8; ++n) acc[n] = mma16(af, ldfrag(VT + sw512b(16 * n + l15, 4 * ks + lq)), acc[n]);
;         }
; #pragma unroll
;         for (int n = 0; n < 8; ++n) HU[(((size_t)u * 8 + w) * 8 + n) * 64 + lane] = (u32x2v){pk2(acc[n][0], acc[n][1]), pk2(acc[n][2], acc[n][3])};
	v_mfma_f32_16x16x32_bf16 v[18:21], v[34:37], v[38:41], v[18:21]
	s_waitcnt lgkmcnt(0)
	v_mfma_f32_16x16x32_bf16 v[22:25], v[34:37], v[42:45], v[22:25]
	ds_read_b128 v[38:41], v173
	ds_read_b128 v[42:45], v174
	s_waitcnt lgkmcnt(1)
	v_mfma_f32_16x16x32_bf16 v[26:29], v[34:37], v[38:41], v[26:29]
	ds_read_b128 v[38:41], v175
	s_waitcnt lgkmcnt(1)
	v_mfma_f32_16x16x32_bf16 v[30:33], v[34:37], v[42:45], v[30:33]
	ds_read_b128 v[42:45], v176
	s_waitcnt lgkmcnt(1)
	v_mfma_f32_16x16x32_bf16 v[2:5], v[34:37], v[38:41], v[2:5]
	ds_read_b128 v[34:37], v177
	ds_read_b128 v[38:41], v178
	s_waitcnt lgkmcnt(1)
	v_mfma_f32_16x16x32_bf16 v[6:9], v[42:45], v[34:37], v[6:9]
	s_waitcnt lgkmcnt(0)
	v_mfma_f32_16x16x32_bf16 v[10:13], v[42:45], v[38:41], v[10:13]
	ds_read_b128 v[34:37], v179
	ds_read_b128 v[38:41], v180
	s_waitcnt lgkmcnt(1)
	v_mfma_f32_16x16x32_bf16 v[14:17], v[42:45], v[34:37], v[14:17]
	s_waitcnt lgkmcnt(0)
	v_mfma_f32_16x16x32_bf16 v[18:21], v[42:45], v[38:41], v[18:21]
	ds_read_b128 v[34:37], v181
	ds_read_b128 v[38:41], v182
	s_waitcnt lgkmcnt(1)
	v_mfma_f32_16x16x32_bf16 v[22:25], v[42:45], v[34:37], v[22:25]
	s_waitcnt lgkmcnt(0)
	v_mfma_f32_16x16x32_bf16 v[26:29], v[42:45], v[38:41], v[26:29]
	ds_read_b128 v[34:37], v183
	ds_read_b128 v[38:41], v184
	s_waitcnt lgkmcnt(1)
	v_mfma_f32_16x16x32_bf16 v[30:33], v[42:45], v[34:37], v[30:33]
	ds_read_b128 v[34:37], v185
	s_waitcnt lgkmcnt(1)
	v_mfma_f32_16x16x32_bf16 v[2:5], v[42:45], v[38:41], v[2:5]
	ds_read_b128 v[38:41], v186
	s_waitcnt lgkmcnt(0)
	v_mfma_f32_16x16x32_bf16 v[6:9], v[34:37], v[38:41], v[6:9]
	ds_read_b128 v[38:41], v187
	ds_read_b128 v[42:45], v188
	s_waitcnt lgkmcnt(1)
	v_mfma_f32_16x16x32_bf16 v[10:13], v[34:37], v[38:41], v[10:13]
	s_waitcnt lgkmcnt(0)
	v_mfma_f32_16x16x32_bf16 v[14:17], v[34:37], v[42:45], v[14:17]
	ds_read_b128 v[38:41], v189
	ds_read_b128 v[42:45], v190
	s_waitcnt lgkmcnt(1)
	v_mfma_f32_16x16x32_bf16 v[18:21], v[34:37], v[38:41], v[18:21]
	s_waitcnt lgkmcnt(0)
	v_mfma_f32_16x16x32_bf16 v[22:25], v[34:37], v[42:45], v[22:25]
	ds_read_b128 v[38:41], v191
	ds_read_b128 v[42:45], v192
	s_waitcnt lgkmcnt(1)
	v_mfma_f32_16x16x32_bf16 v[26:29], v[34:37], v[38:41], v[26:29]
	ds_read_b128 v[38:41], v194
	ds_read_b128 v[46:49], v193
	ds_read_b128 v[50:53], v195
	ds_read_b128 v[62:65], v196
	s_waitcnt lgkmcnt(1)
	v_mfma_f32_16x16x32_bf16 v[6:9], v[38:41], v[50:53], v[6:9]
	v_mfma_f32_16x16x32_bf16 v[30:33], v[34:37], v[42:45], v[30:33]
	s_nop 6
	v_cvt_pk_bf16_f32 v6, v6, v7
	v_cvt_pk_bf16_f32 v7, v8, v9
	v_lshlrev_b64 v[8:9], 15, v[80:81]
	v_mfma_f32_16x16x32_bf16 v[2:5], v[34:37], v[46:49], v[2:5]
	v_lshl_add_u64 v[34:35], v[60:61], 0, v[8:9]
	ds_read_b128 v[42:45], v197
	ds_read_b128 v[66:69], v198
	ds_read_b128 v[70:73], v199
	ds_read_b128 v[74:77], v200
	ds_read_b128 v[50:53], v201
	ds_read_b128 v[82:85], v203
	global_store_dwordx2 v[34:35], v[6:7], off sc1
	s_waitcnt lgkmcnt(6)
	v_mfma_f32_16x16x32_bf16 v[6:9], v[38:41], v[62:65], v[10:13]
	s_waitcnt lgkmcnt(0)
	v_mfma_f32_16x16x32_bf16 v[2:5], v[38:41], v[82:85], v[2:5]
	s_nop 5
	v_cvt_pk_bf16_f32 v6, v6, v7
	v_cvt_pk_bf16_f32 v7, v8, v9
	global_store_dwordx2 v[34:35], v[6:7], off offset:512 sc1
	v_mfma_f32_16x16x32_bf16 v[6:9], v[38:41], v[42:45], v[14:17]
	v_cvt_pk_bf16_f32 v2, v2, v3
	v_cvt_pk_bf16_f32 v3, v4, v5
	global_store_dwordx2 v[34:35], v[2:3], off offset:3584 sc1
	s_nop 4
	v_cvt_pk_bf16_f32 v6, v6, v7
	v_cvt_pk_bf16_f32 v7, v8, v9
	global_store_dwordx2 v[34:35], v[6:7], off offset:1024 sc1
	v_mfma_f32_16x16x32_bf16 v[6:9], v[38:41], v[66:69], v[18:21]
	s_nop 7
	v_cvt_pk_bf16_f32 v6, v6, v7
	v_cvt_pk_bf16_f32 v7, v8, v9
	global_store_dwordx2 v[34:35], v[6:7], off offset:1536 sc1
	v_mfma_f32_16x16x32_bf16 v[6:9], v[38:41], v[70:73], v[22:25]
	s_nop 7
	v_cvt_pk_bf16_f32 v6, v6, v7
	v_cvt_pk_bf16_f32 v7, v8, v9
	global_store_dwordx2 v[34:35], v[6:7], off offset:2048 sc1
	v_mfma_f32_16x16x32_bf16 v[6:9], v[38:41], v[74:77], v[26:29]
	s_nop 7
	v_cvt_pk_bf16_f32 v6, v6, v7
	v_cvt_pk_bf16_f32 v7, v8, v9
	global_store_dwordx2 v[34:35], v[6:7], off offset:2560 sc1
	v_mfma_f32_16x16x32_bf16 v[6:9], v[38:41], v[50:53], v[30:33]
	s_nop 7
	v_cvt_pk_bf16_f32 v6, v6, v7
	v_cvt_pk_bf16_f32 v7, v8, v9
	global_store_dwordx2 v[34:35], v[6:7], off offset:3072 sc1
	s_barrier
	s_cbranch_scc0 .LBB0_575

; #define LAS __attribute__((address_space(3)))
; __device__ __forceinline__ void hgrn_passA(Frame& F, u32x2v* HU, float* HD) {
;     ...
; #pragma unroll 8
;         for (int s2 = 0; s2 < 32; ++s2) { const f32x4 t0 = *(const LAS f32x4*)(segtot + s2 * 128 + 8 * c8), t1 = *(const LAS f32x4*)(segtot + s2 * 128 + 8 * c8 + 4);
;             aend[0] += t0; aend[1] += t1; if (s2 < tq) { off[0] += t0; off[1] += t1; } }
.LBB0_570:
	ds_read_b128 v[10:13], v80
	ds_read_b128 v[14:17], v80 offset:16
	ds_read_b128 v[22:25], v80 offset:512
	ds_read_b128 v[18:21], v80 offset:528
	ds_read_b128 v[204:207], v80 offset:1024
	ds_read_b128 v[208:211], v80 offset:1040
	ds_read_b128 v[212:215], v80 offset:1536
	ds_read_b128 v[216:219], v80 offset:1552
	ds_read_b128 v[220:223], v80 offset:2048
	ds_read_b128 v[224:227], v80 offset:2064
	s_waitcnt lgkmcnt(9)
	v_pk_add_f32 v[46:47], v[46:47], v[12:13]
	v_pk_add_f32 v[88:89], v[88:89], v[10:11]
	s_waitcnt lgkmcnt(8)
	v_pk_add_f32 v[68:69], v[68:69], v[16:17]
	v_pk_add_f32 v[70:71], v[70:71], v[14:15]
	v_pk_add_f32 v[14:15], v[74:75], v[14:15]
	v_cmp_lt_u32_e64 s[0:1], s5, v112
	v_pk_add_f32 v[12:13], v[90:91], v[12:13]
	v_pk_add_f32 v[10:11], v[96:97], v[10:11]
	v_pk_add_f32 v[16:17], v[72:73], v[16:17]
	s_add_i32 s9, s5, 1
	ds_read_b128 v[228:231], v80 offset:2560
	ds_read_b128 v[232:235], v80 offset:2576
	v_cndmask_b32_e64 v15, v75, v15, s[0:1]
	v_cndmask_b32_e64 v14, v74, v14, s[0:1]
	v_cndmask_b32_e64 v17, v73, v17, s[0:1]
	v_cndmask_b32_e64 v16, v72, v16, s[0:1]
	v_cndmask_b32_e64 v11, v97, v11, s[0:1]
	v_cndmask_b32_e64 v10, v96, v10, s[0:1]
	v_cndmask_b32_e64 v13, v91, v13, s[0:1]
	v_cndmask_b32_e64 v12, v90, v12, s[0:1]
	ds_read_b128 v[236:239], v80 offset:3072
	ds_read_b128 v[240:243], v80 offset:3088
	s_waitcnt lgkmcnt(11)
	v_pk_add_f32 v[46:47], v[46:47], v[24:25]
	v_pk_add_f32 v[72:73], v[88:89], v[22:23]
	s_waitcnt lgkmcnt(10)
	v_pk_add_f32 v[68:69], v[68:69], v[20:21]
	v_pk_add_f32 v[70:71], v[70:71], v[18:19]
	v_pk_add_f32 v[24:25], v[12:13], v[24:25]
	v_pk_add_f32 v[22:23], v[10:11], v[22:23]
	v_pk_add_f32 v[20:21], v[16:17], v[20:21]
	v_pk_add_f32 v[18:19], v[14:15], v[18:19]
	v_cmp_lt_u32_e64 s[0:1], s9, v112
	s_add_i32 s10, s5, 2
	ds_read_b128 v[244:247], v80 offset:3584
	ds_read_b128 v[248:251], v80 offset:3600
	s_waitcnt lgkmcnt(11)
	v_pk_add_f32 v[46:47], v[46:47], v[206:207]
	v_pk_add_f32 v[72:73], v[72:73], v[204:205]
	s_waitcnt lgkmcnt(10)
	v_pk_add_f32 v[68:69], v[68:69], v[210:211]
	v_pk_add_f32 v[70:71], v[70:71], v[208:209]
	v_cndmask_b32_e64 v15, v15, v19, s[0:1]
	v_cndmask_b32_e64 v14, v14, v18, s[0:1]
	v_cndmask_b32_e64 v17, v17, v21, s[0:1]
	v_cndmask_b32_e64 v16, v16, v20, s[0:1]
	v_cndmask_b32_e64 v11, v11, v23, s[0:1]
	v_cndmask_b32_e64 v10, v10, v22, s[0:1]
	v_cndmask_b32_e64 v13, v13, v25, s[0:1]
	v_cndmask_b32_e64 v12, v12, v24, s[0:1]
	s_waitcnt lgkmcnt(9)
	v_pk_add_f32 v[18:19], v[46:47], v[214:215]
	v_pk_add_f32 v[20:21], v[72:73], v[212:213]
	s_waitcnt lgkmcnt(8)
	v_pk_add_f32 v[22:23], v[68:69], v[218:219]
	v_pk_add_f32 v[24:25], v[70:71], v[216:217]
	v_pk_add_f32 v[46:47], v[12:13], v[206:207]
	v_pk_add_f32 v[68:69], v[10:11], v[204:205]
	v_pk_add_f32 v[70:71], v[16:17], v[210:211]
	v_pk_add_f32 v[72:73], v[14:15], v[208:209]
	v_cmp_lt_u32_e64 s[0:1], s10, v112
	s_add_i32 s11, s5, 3
	s_waitcnt lgkmcnt(7)
	v_pk_add_f32 v[18:19], v[18:19], v[222:223]
	v_pk_add_f32 v[20:21], v[20:21], v[220:221]
	s_waitcnt lgkmcnt(6)
	v_pk_add_f32 v[22:23], v[22:23], v[226:227]
	v_pk_add_f32 v[24:25], v[24:25], v[224:225]
	v_cndmask_b32_e64 v15, v15, v73, s[0:1]
	v_cndmask_b32_e64 v14, v14, v72, s[0:1]
	v_cndmask_b32_e64 v17, v17, v71, s[0:1]
	v_cndmask_b32_e64 v16, v16, v70, s[0:1]
	v_cndmask_b32_e64 v11, v11, v69, s[0:1]
	v_cndmask_b32_e64 v10, v10, v68, s[0:1]
	v_cndmask_b32_e64 v13, v13, v47, s[0:1]
	v_cndmask_b32_e64 v12, v12, v46, s[0:1]
	s_waitcnt lgkmcnt(5)
	v_pk_add_f32 v[18:19], v[18:19], v[230:231]
	v_pk_add_f32 v[20:21], v[20:21], v[228:229]
	s_waitcnt lgkmcnt(4)
	v_pk_add_f32 v[22:23], v[22:23], v[234:235]
	v_pk_add_f32 v[24:25], v[24:25], v[232:233]
	v_pk_add_f32 v[46:47], v[12:13], v[214:215]
	v_pk_add_f32 v[68:69], v[10:11], v[212:213]
	v_pk_add_f32 v[70:71], v[16:17], v[218:219]
	v_pk_add_f32 v[72:73], v[14:15], v[216:217]
	v_cmp_lt_u32_e64 s[0:1], s11, v112
	s_add_i32 s12, s5, 4
	s_waitcnt lgkmcnt(3)
	v_pk_add_f32 v[18:19], v[18:19], v[238:239]
	v_pk_add_f32 v[20:21], v[20:21], v[236:237]
	s_waitcnt lgkmcnt(2)
	v_pk_add_f32 v[22:23], v[22:23], v[242:243]
	v_pk_add_f32 v[24:25], v[24:25], v[240:241]
	v_cndmask_b32_e64 v15, v15, v73, s[0:1]
	v_cndmask_b32_e64 v14, v14, v72, s[0:1]
	v_cndmask_b32_e64 v17, v17, v71, s[0:1]
	v_cndmask_b32_e64 v16, v16, v70, s[0:1]
	v_cndmask_b32_e64 v11, v11, v69, s[0:1]
	v_cndmask_b32_e64 v10, v10, v68, s[0:1]
	v_cndmask_b32_e64 v13, v13, v47, s[0:1]
	v_cndmask_b32_e64 v12, v12, v46, s[0:1]
	s_waitcnt lgkmcnt(1)
	v_pk_add_f32 v[46:47], v[18:19], v[246:247]
	v_pk_add_f32 v[88:89], v[20:21], v[244:245]
	s_waitcnt lgkmcnt(0)
	v_pk_add_f32 v[68:69], v[22:23], v[250:251]
	v_pk_add_f32 v[70:71], v[24:25], v[248:249]
	v_pk_add_f32 v[18:19], v[12:13], v[222:223]
	v_pk_add_f32 v[20:21], v[10:11], v[220:221]
	v_pk_add_f32 v[22:23], v[16:17], v[226:227]
	v_pk_add_f32 v[24:25], v[14:15], v[224:225]
	v_cmp_lt_u32_e64 s[0:1], s12, v112
	s_add_i32 s13, s5, 5
	s_add_i32 s14, s5, 6
	v_cndmask_b32_e64 v15, v15, v25, s[0:1]
	v_cndmask_b32_e64 v14, v14, v24, s[0:1]
	v_cndmask_b32_e64 v17, v17, v23, s[0:1]
	v_cndmask_b32_e64 v16, v16, v22, s[0:1]
	v_cndmask_b32_e64 v11, v11, v21, s[0:1]
	v_cndmask_b32_e64 v10, v10, v20, s[0:1]
	v_cndmask_b32_e64 v13, v13, v19, s[0:1]
	v_cndmask_b32_e64 v12, v12, v18, s[0:1]
	v_pk_add_f32 v[18:19], v[12:13], v[230:231]
	v_pk_add_f32 v[20:21], v[10:11], v[228:229]
	v_pk_add_f32 v[22:23], v[16:17], v[234:235]
	v_pk_add_f32 v[24:25], v[14:15], v[232:233]
	v_cmp_lt_u32_e64 s[0:1], s13, v112
	s_add_i32 s15, s5, 7
	s_add_i32 s5, s5, 8
	v_cndmask_b32_e64 v15, v15, v25, s[0:1]
	v_cndmask_b32_e64 v14, v14, v24, s[0:1]
	v_cndmask_b32_e64 v17, v17, v23, s[0:1]
	v_cndmask_b32_e64 v16, v16, v22, s[0:1]
	v_cndmask_b32_e64 v11, v11, v21, s[0:1]
	v_cndmask_b32_e64 v10, v10, v20, s[0:1]
	v_cndmask_b32_e64 v13, v13, v19, s[0:1]
	v_cndmask_b32_e64 v12, v12, v18, s[0:1]
	v_pk_add_f32 v[18:19], v[12:13], v[238:239]
	v_pk_add_f32 v[20:21], v[10:11], v[236:237]
	v_pk_add_f32 v[22:23], v[16:17], v[242:243]
	v_pk_add_f32 v[24:25], v[14:15], v[240:241]
	v_cmp_lt_u32_e64 s[0:1], s14, v112
	v_add_u32_e32 v80, 0x1000, v80
	s_cmp_eq_u32 s5, 32
	v_cndmask_b32_e64 v15, v15, v25, s[0:1]
	v_cndmask_b32_e64 v14, v14, v24, s[0:1]
	v_cndmask_b32_e64 v17, v17, v23, s[0:1]
	v_cndmask_b32_e64 v16, v16, v22, s[0:1]
	v_cndmask_b32_e64 v11, v11, v21, s[0:1]
	v_cndmask_b32_e64 v10, v10, v20, s[0:1]
	v_cndmask_b32_e64 v13, v13, v19, s[0:1]
	v_cndmask_b32_e64 v12, v12, v18, s[0:1]
	v_pk_add_f32 v[18:19], v[12:13], v[246:247]
	v_pk_add_f32 v[20:21], v[10:11], v[244:245]
	v_pk_add_f32 v[22:23], v[16:17], v[250:251]
	v_pk_add_f32 v[24:25], v[14:15], v[248:249]
	v_cmp_lt_u32_e64 s[0:1], s15, v112
	s_nop 1
	v_cndmask_b32_e64 v74, v14, v24, s[0:1]
	v_cndmask_b32_e64 v75, v15, v25, s[0:1]
	v_cndmask_b32_e64 v72, v16, v22, s[0:1]
	v_cndmask_b32_e64 v73, v17, v23, s[0:1]
	v_cndmask_b32_e64 v96, v10, v20, s[0:1]
	v_cndmask_b32_e64 v97, v11, v21, s[0:1]
	v_cndmask_b32_e64 v90, v12, v18, s[0:1]
	v_cndmask_b32_e64 v91, v13, v19, s[0:1]
	s_cbranch_scc0 .LBB0_570
; #define GAS __attribute__((address_space(1)))
; #define LAS __attribute__((address_space(3)))
; __device__ __forceinline__ void hgrn_passA(Frame& F, u32x2v* HU, float* HD) {
;     ...
;         __syncthreads();
;         if (tq == 0) { f32x4 d0, d1;
; #pragma unroll
;             for (int e = 0; e < 4; ++e) { d0[e] = __expf(aend[0][e]); d1[e] = __expf(aend[1][e]); }
;             *(GAS f32x4*)(HD + (size_t)u * 128 + 8 * c8) = d0; *(GAS f32x4*)(HD + (size_t)u * 128 + 8 * c8 + 4) = d1; }
; __device__ __forceinline__ void xattn_prompt(Frame& F) {
;     LAS unsigned char* KS = F.lds;
;     LAS unsigned char* VT = F.lds + 32768;
;     const int tid = F.tid, w = F.wave, lane = F.lane, l15 = lane & 15, lq = lane >> 4;
;     for (int u = blockIdx.x; u < 256; u += F.G) {
;         const int qb = u & 7, bh = u >> 3, b = bh >> 2, h = bh & 3;
;         { const int kv = tid >> 1, half = tid & 1; const bf16* src = F.KVB + (size_t)(b * 256 + kv) * 512 + h * 64 + half * 32;
; #pragma unroll
;           for (int j = 0; j < 4; ++j) { const int cidx = 4 * half + j; *(LAS v4u*)(KS + ((((kv >> 4) * 2 + (cidx >> 2)) * 64 + 16 * (cidx & 3) + (kv & 15)) << 4)) = *(const GAS v4u*)(src + 8 * j); } }
	s_barrier
	s_and_saveexec_b64 s[0:1], vcc
	s_xor_b64 s[0:1], exec, s[0:1]
	s_ashr_i32 s5, s4, 31
	s_or_saveexec_b64 s[0:1], s[0:1]
	v_mov_b64_e32 v[80:81], s[4:5]
	s_xor_b64 exec, exec, s[0:1]
	s_cbranch_execz .LBB0_568
	v_mul_f32_e32 v11, 0x3fb8aa3b, v70
	v_mul_f32_e32 v12, 0x3fb8aa3b, v71
	v_mul_f32_e32 v13, 0x3fb8aa3b, v68
	v_mul_f32_e32 v10, 0x3fb8aa3b, v88
	v_exp_f32_e32 v14, v11
	v_mul_f32_e32 v11, 0x3fb8aa3b, v89
	v_exp_f32_e32 v15, v12
	v_mul_f32_e32 v12, 0x3fb8aa3b, v46
	v_exp_f32_e32 v16, v13
	v_mul_f32_e32 v13, 0x3fb8aa3b, v47
	v_exp_f32_e32 v10, v10
	v_exp_f32_e32 v11, v11
	v_exp_f32_e32 v12, v12
	v_exp_f32_e32 v13, v13
	v_mul_f32_e32 v17, 0x3fb8aa3b, v69
	v_exp_f32_e32 v17, v17
	s_ashr_i32 s5, s4, 31
	s_lshl_b64 s[10:11], s[4:5], 9
	v_lshl_add_u64 v[18:19], v[58:59], 0, s[10:11]
	v_mov_b64_e32 v[80:81], s[4:5]
	global_store_dwordx4 v[18:19], v[10:13], off sc1
	global_store_dwordx4 v[18:19], v[14:17], off offset:16 sc1
	s_branch .LBB0_568
.LBB0_575:
	s_waitcnt vmcnt(0)
	s_barrier
	v_cmp_eq_u32_e32 vcc, 0, v0
	s_and_saveexec_b64 s[0:1], vcc
	s_cbranch_execz .Lpa_rel_done
	v_readlane_b32 s2, v254, 19
	v_readlane_b32 s3, v254, 20
	s_lshl_b32 s4, s88, 2
	s_add_u32 s2, s2, s4
	s_addc_u32 s3, s3, 0
	s_add_u32 s2, s2, 0x4000
	s_addc_u32 s3, s3, 0
	v_mov_b32_e32 v2, 0
	v_mov_b32_e32 v3, 1
	global_atomic_add v2, v3, s[2:3]
.Lpa_rel_done:
	s_or_b64 exec, exec, s[0:1]
	v_mbcnt_lo_u32_b32 v5, -1, 0
	v_mbcnt_hi_u32_b32 v5, -1, v5
	v_and_b32_e32 v7, 64, v5
	v_xor_b32_e32 v6, 16, v5
	v_add_u32_e32 v7, 64, v7
	v_cmp_lt_i32_e32 vcc, v6, v7
	v_lshrrev_b32_e32 v47, 1, v0
	v_and_b32_e32 v3, 1, v0
	v_cndmask_b32_e32 v6, v5, v6, vcc
	v_lshlrev_b32_e32 v82, 2, v6
	v_xor_b32_e32 v6, 32, v5
	v_cmp_lt_i32_e32 vcc, v6, v7
	v_lshrrev_b32_e32 v4, 6, v0
	v_lshlrev_b32_e32 v2, 5, v3
	v_cndmask_b32_e32 v5, v5, v6, vcc
	v_mov_b32_e32 v15, 0
	v_and_or_b32 v3, v112, 30, v3
	v_lshlrev_b32_e32 v80, 5, v4
	v_and_or_b32 v4, v47, 24, v4
	v_lshlrev_b32_e32 v83, 2, v5
	v_lshlrev_b32_e32 v5, 4, v0
	v_readlane_b32 s4, v255, 3
	v_readlane_b32 s0, v254, 39
	v_lshlrev_b32_e32 v14, 3, v55
	v_and_b32_e32 v6, 0xf0, v111
	v_lshl_add_u32 v3, v3, 10, 0
	v_and_b32_e32 v7, 0xf0, v5
	v_lshl_add_u32 v8, v4, 10, 0
	v_lshlrev_b32_e32 v4, 4, v55
	v_mov_b32_e32 v5, v15
	v_readlane_b32 s5, v255, 4
	s_mov_b32 s1, 0
	v_lshl_add_u32 v81, v202, 4, 0
	s_lshl_b32 s2, s0, 5
	v_lshl_add_u64 v[16:17], s[4:5], 0, v[4:5]
	v_lshl_add_u64 v[18:19], s[38:39], 0, v[14:15]
	v_lshlrev_b32_e32 v14, 1, v2
	v_add_u32_e32 v84, v3, v6
	v_lshlrev_b32_e32 v20, 1, v202
	s_movk_i32 s3, 0x1000
	s_movk_i32 s8, 0x2000
	s_movk_i32 s9, 0x3000
	s_movk_i32 s10, 0x4000
	s_movk_i32 s11, 0x5000
	s_movk_i32 s12, 0x6000
	s_movk_i32 s13, 0x7000
	v_add_u32_e32 v85, v8, v7
	s_mov_b32 s14, s88

; __device__ __forceinline__ unsigned xb_ld(unsigned* p)              { return __hip_atomic_load(p, __ATOMIC_RELAXED, __HIP_MEMORY_SCOPE_AGENT); }
; __device__ __forceinline__ unsigned xb_add(unsigned* p, unsigned v) { return __hip_atomic_fetch_add(p, v, __ATOMIC_RELAXED, __HIP_MEMORY_SCOPE_AGENT); }
; #define XB_SPIN(cond, bar) do { unsigned _sp = 0; while (cond) { __builtin_amdgcn_s_sleep(1); \
;     if ((++_sp & 255u) == 0u) { if (xb_ld(&(bar)[XB_TMO])) break; if (_sp > XB_SPIN_CAP) { atomicAdd(&(bar)[XB_TMO], 1u); break; } } } } while (0)
; __device__ __forceinline__ void xcd_barrier(const XcdBarrier& b) {
;     asm volatile("s_waitcnt vmcnt(0)" ::: "memory");
;     __syncthreads();
;     if (threadIdx.x == 0) {
;         unsigned* bar = b.bar;
;         __builtin_amdgcn_s_waitcnt(0);
;         unsigned nloc = b.st[0], nx = b.st[1];
;         if (nloc == 0u) { xcd_barrier_complete(bar, b.x, nloc, nx); b.st[0] = nloc; b.st[1] = nx; }
;         const unsigned old = xb_add(&bar[XB_XSUB(b.x)], 1u);
;         const unsigned gen = old / nloc;
;         if (old + 1u == (gen + 1u) * nloc) {
;             __builtin_amdgcn_fence(__ATOMIC_RELEASE, "agent");
;             asm volatile("s_waitcnt vmcnt(0)" ::: "memory");
;             const unsigned og = xb_add(&bar[XB_TOP], 1u);
;             const unsigned tg = og / nx;
;             if (og + 1u == (tg + 1u) * nx) xb_add(&bar[XB_TOPGEN], 1u);
;             else XB_SPIN(xb_ld(&bar[XB_TOPGEN]) == tg, bar);
;             __builtin_amdgcn_fence(__ATOMIC_ACQUIRE, "agent");
;             xb_add(&bar[XB_XGEN(b.x)], 1u);
;             asm volatile("s_waitcnt vmcnt(0)" ::: "memory");
;         } else {
;             XB_SPIN(xb_ld(&bar[XB_XGEN(b.x)]) == gen, bar);
;             __builtin_amdgcn_fence(__ATOMIC_ACQUIRE, "agent");
;             asm volatile("s_waitcnt vmcnt(0)" ::: "memory");
;         }
;     }
;     __syncthreads();
; }
.LBB0_579:
	s_cmp_gt_i32 s71, 3
	s_cselect_b64 s[0:1], -1, 0
	s_and_b64 s[2:3], s[6:7], s[0:1]
	s_andn2_b64 vcc, exec, s[2:3]
	s_cbranch_vccnz .LBB0_629
	s_waitcnt lgkmcnt(0)
	s_barrier

; #define PC_LOAD_LF(LF, ckk) do { const size_t rb_ = (size_t)(b * 2048 + sc * 256 + (ckk) * 64 + seg * 16) * 512 + h * 128 + c; \
;     _Pragma("unroll") for (int i = 0; i < 16; ++i) LF[i] = F.LOGF[rb_ + (size_t)i * 512]; } while (0)
; __device__ __forceinline__ void hgrn_passC(Frame& F, const u32x2v* HU, const float* HD) {
;     ...
;     const int tid = F.tid, c = tid & 127, seg = tid >> 7, w = F.wave, lane = F.lane, l15 = lane & 15, lq = lane >> 4;
;     const int tb = w >> 1, wh = w & 1;
;     for (int u = blockIdx.x; u < HG_NU; u += F.G) {
;         const int sc = u & 7, bh = u >> 3, b = bh >> 2, h = bh & 3;
;         _Float16 lfA[16], lfB[16]; bf16 qA_[16], kA_[16], vA_[16], qB_[16], kB_[16], vB_[16];
;         PC_LOAD_LF(lfA, 0);
;         float og[4];
; #pragma unroll
;         for (int n = 0; n < 4; ++n) og[n] = F.onorm_g[h * 128 + 16 * (4 * wh + n) + l15];
;         f32x4 S[8];
; #pragma unroll
;         for (int n = 0; n < 8; ++n) S[n] = (f32x4){0.f, 0.f, 0.f, 0.f};
;         { int p = 0;
;     ...
;           for (; p < sc; p += 3) { const int up = (bh << 3) + p;
;               const bool v1 = p + 1 < sc, v2 = p + 2 < sc; const int u1 = v1 ? up + 1 : up, u2 = v2 ? up + 2 : up;
;               const f32x4 one = (f32x4){1.f, 1.f, 1.f, 1.f}, zero = (f32x4){0.f, 0.f, 0.f, 0.f};
;               const f32x4 da = *(const f32x4*)(HD + (size_t)up * 128 + 16 * w + 4 * lq), db0 = *(const f32x4*)(HD + (size_t)u1 * 128 + 16 * w + 4 * lq), dc0 = *(const f32x4*)(HD + (size_t)u2 * 128 + 16 * w + 4 * lq);
;               const f32x4 db = v1 ? db0 : one, dc = v2 ? dc0 : one;
;               u32x2v ua[8], ub[8], uc[8];
; #pragma unroll
;               for (int n = 0; n < 8; ++n) { ua[n] = HU[(((size_t)up * 8 + w) * 8 + n) * 64 + lane]; ub[n] = HU[(((size_t)u1 * 8 + w) * 8 + n) * 64 + lane]; uc[n] = HU[(((size_t)u2 * 8 + w) * 8 + n) * 64 + lane]; }
; #pragma unroll
;               for (int n = 0; n < 8; ++n) S[n] = ((S[n] * da + HU_F4(ua[n])) * db + (v1 ? HU_F4(ub[n]) : zero)) * dc + (v2 ? HU_F4(uc[n]) : zero); } }
.LBB0_644:
	s_cmpk_gt_i32 s88, 0xff
	s_cbranch_scc1 .LBB0_690
	s_and_b32 s2, s88, 7
	s_cmp_eq_u32 s2, 0
	s_cbranch_scc1 .Lpc_acq_done
	v_readlane_b32 s0, v254, 19
	v_readlane_b32 s1, v254, 20
	s_and_b32 s3, s88, 0xf8
	s_lshl_b32 s3, s3, 2
	s_add_u32 s0, s0, s3
	s_addc_u32 s1, s1, 0
	s_add_u32 s0, s0, 0x4000
	s_addc_u32 s1, s1, 0
	v_and_b32_e32 v3, 7, v202
	v_lshlrev_b32_e32 v2, 2, v3
	s_mov_b32 s3, 0
.Lpc_acq_loop:
	global_load_dword v4, v2, s[0:1] sc1
	s_waitcnt vmcnt(0)
	v_cmp_eq_u32_e32 vcc, 0, v4
	v_cmp_gt_u32_e64 s[4:5], s2, v3
	s_and_b64 s[4:5], vcc, s[4:5]
	s_cbranch_scc0 .Lpc_acq_ok
	s_sleep 1
	s_add_i32 s3, s3, 1
	s_cmpk_lt_u32 s3, 0x2000
	s_cbranch_scc1 .Lpc_acq_loop
.Lpc_acq_ok:
	buffer_inv sc1
.Lpc_acq_done:
	v_readlane_b32 s5, v254, 39
	v_and_b32_e32 v11, 15, v0
	s_lshl_b32 s6, s5, 4
	v_or_b32_e32 v22, s6, v11
	v_lshl_add_u32 v136, v22, 7, 0
	v_mbcnt_lo_u32_b32 v22, -1, 0
	v_mbcnt_hi_u32_b32 v22, -1, v22
	v_and_b32_e32 v24, 64, v22
	v_xor_b32_e32 v23, 1, v22
	v_add_u32_e32 v24, 64, v24
	v_cmp_lt_i32_e32 vcc, v23, v24
	v_readlane_b32 s48, v254, 0
	s_lshr_b32 s3, s48, 7
	v_cndmask_b32_e32 v23, v22, v23, vcc
	s_bfe_u32 s2, s48, 0x10006
	s_lshl_b32 s4, s5, 6
	v_lshlrev_b32_e32 v138, 2, v23
	v_xor_b32_e32 v23, 2, v22
	s_add_u32 s0, s68, s4
	v_cmp_lt_i32_e32 vcc, v23, v24
	v_mov_b32_e32 v69, 0
	s_addc_u32 s1, s69, 0
	v_and_b32_e32 v68, 48, v202
	v_cndmask_b32_e32 v23, v22, v23, vcc
	v_lshl_add_u64 v[2:3], s[0:1], 0, v[68:69]
	s_lshl_b32 s0, s5, 1
	v_lshrrev_b32_e32 v8, 5, v202
	v_lshlrev_b32_e32 v139, 2, v23
	v_xor_b32_e32 v23, 4, v22
	v_bitop3_b32 v8, s0, v11, v8 bitop3:0x36
	v_cmp_lt_i32_e32 vcc, v23, v24
	v_lshlrev_b32_e32 v12, 8, v11
	v_lshlrev_b32_e32 v8, 4, v8
	s_add_i32 s30, 0, 0x12000
	v_cndmask_b32_e32 v23, v22, v23, vcc
	v_and_b32_e32 v66, 0x7f, v0
	v_add3_u32 v13, s30, v8, v12
	v_lshrrev_b32_e32 v8, 1, v202
	v_lshlrev_b32_e32 v140, 2, v23
	v_xor_b32_e32 v23, 8, v22
	s_lshl_b32 s74, s5, 3
	v_and_b32_e32 v14, 8, v8
	s_add_i32 s0, 0, 0x1a200
	v_lshlrev_b32_e32 v8, 2, v66
	s_add_i32 s5, 0, 0x1a000
	v_cmp_lt_i32_e32 vcc, v23, v24
	v_lshrrev_b32_e32 v7, 7, v0
	v_add_u32_e32 v130, s0, v8
	v_add_u32_e32 v131, s5, v8
	v_lshlrev_b32_e32 v8, 1, v0
	v_cndmask_b32_e32 v22, v22, v23, vcc
	v_lshlrev_b32_e32 v67, 4, v7
	s_movk_i32 s12, 0x80
	v_lshlrev_b32_e32 v9, 1, v7
	v_lshlrev_b32_e32 v141, 2, v22
	v_lshlrev_b32_e32 v7, 12, v7
	v_and_b32_e32 v22, 0xf0, v8
	v_lshl_add_u32 v71, v0, 2, s0
	v_cmp_gt_u32_e64 s[0:1], s12, v0
	v_bitop3_b32 v31, v22, s12, v7 bitop3:0x36
	s_movk_i32 s12, 0x90
	v_bitop3_b32 v32, v22, s12, v7 bitop3:0x36
	s_movk_i32 s12, 0xa0
	v_bitop3_b32 v33, v22, s12, v7 bitop3:0x36
	s_movk_i32 s12, 0xb0
	s_movk_i32 s14, 0x50
	v_bitop3_b32 v34, v22, s12, v7 bitop3:0x36
	s_movk_i32 s12, 0xc0
	v_bitop3_b32 v28, v22, s14, v7 bitop3:0x36
	s_movk_i32 s14, 0x60
	v_bitop3_b32 v35, v22, s12, v7 bitop3:0x36
	s_movk_i32 s12, 0xd0
	v_lshrrev_b32_e32 v10, 4, v202
	s_lshl_b32 s7, s3, 12
	s_movk_i32 s13, 0xf0
	v_bitop3_b32 v29, v22, s14, v7 bitop3:0x36
	s_movk_i32 s14, 0x70
	v_bitop3_b32 v36, v22, s12, v7 bitop3:0x36
	s_movk_i32 s12, 0xe0
	s_add_i32 s7, s7, 0
	v_or_b32_e32 v23, v22, v7
	v_bitop3_b32 v24, v22, 16, v7 bitop3:0x36
	v_bitop3_b32 v25, v22, 32, v7 bitop3:0x36
	v_bitop3_b32 v26, v22, 48, v7 bitop3:0x36
	v_bitop3_b32 v27, v22, 64, v7 bitop3:0x36
	v_bitop3_b32 v30, v22, s14, v7 bitop3:0x36
	v_bitop3_b32 v22, v22, s12, v7 bitop3:0x36
	v_bitop3_b32 v37, v8, s13, v7 bitop3:0x26
	v_bitop3_b32 v7, v10, v0, 15 bitop3:0x78
	v_add_u32_e32 v133, s7, v12
	s_lshl_b32 s7, s3, 11
	s_add_i32 s31, 0, 0x10000
	v_lshlrev_b32_e32 v143, 4, v7
	v_bitop3_b32 v7, v10, v11, 4 bitop3:0x36
	v_lshlrev_b32_e32 v6, 2, v10
	v_lshlrev_b32_e32 v21, 7, v11
	s_add_i32 s7, s31, s7
	v_lshlrev_b32_e32 v144, 4, v7
	v_bitop3_b32 v7, v10, v11, 8 bitop3:0x36
	v_lshl_or_b32 v132, s3, 4, v6
	v_add_u32_e32 v134, s7, v21
	s_lshl_b32 s7, s2, 2
	v_lshlrev_b32_e32 v145, 4, v7
	v_bitop3_b32 v7, v10, v11, 12 bitop3:0x36
	s_add_i32 s43, s7, 0
	v_lshlrev_b32_e32 v146, 4, v7
	v_lshl_or_b32 v7, s2, 5, v11
	v_or_b32_e32 v148, 2, v132
	v_or_b32_e32 v149, 3, v132
	v_and_b32_e32 v15, 14, v8
	s_lshl_b32 s20, s2, 1
	s_add_i32 s5, s5, s4
	s_add_i32 s43, s43, 0x1aa00
	v_lshrrev_b32_e32 v8, 3, v7
	v_lshlrev_b32_e32 v39, 1, v10
	v_lshrrev_b32_e32 v44, 1, v148
	v_lshrrev_b32_e32 v46, 1, v149
	v_lshrrev_b32_e32 v18, 1, v0
	v_bfe_u32 v19, v0, 1, 3
	s_cmp_le_u32 s20, s3
	v_xor_b32_e32 v40, v8, v39
	v_or_b32_e32 v147, 1, v132
	v_bitop3_b32 v45, v44, v8, 7 bitop3:0x6c
	v_bitop3_b32 v8, v46, v8, 7 bitop3:0x6c
	v_lshlrev_b32_e32 v17, 7, v66
	v_bitop3_b32 v20, v18, v9, 7 bitop3:0x6c
	v_bitop3_b32 v9, v9, v19, 1 bitop3:0x36
	s_cselect_b64 s[62:63], -1, 0
	v_cmp_gt_u32_e64 s[12:13], v7, v132
	v_cmp_gt_u32_e64 s[14:15], v7, v147
	v_cmp_gt_u32_e64 s[16:17], v7, v148
	v_cmp_gt_u32_e64 s[18:19], v7, v149
	v_lshlrev_b32_e32 v7, 7, v149
	v_lshlrev_b32_e32 v8, 4, v8
	s_or_b32 s21, s20, 1
	v_lshl_or_b32 v20, v20, 4, v17
	v_lshl_or_b32 v17, v9, 4, v17
; #define PC_LOAD_LF(LF, ckk) do { const size_t rb_ = (size_t)(b * 2048 + sc * 256 + (ckk) * 64 + seg * 16) * 512 + h * 128 + c; \
;     _Pragma("unroll") for (int i = 0; i < 16; ++i) LF[i] = F.LOGF[rb_ + (size_t)i * 512]; } while (0)
; #define PC_LOAD_QKV(QQ, KQ, VQ, ckk) do { const size_t rb_ = (size_t)(b * 2048 + sc * 256 + (ckk) * 64 + seg * 16) * 512 + h * 128 + c; \
;     _Pragma("unroll") for (int i = 0; i < 16; ++i) { QQ[i] = F.Q[rb_ + (size_t)i * 512]; VQ[i] = F.V[rb_ + (size_t)i * 512]; } } while (0)
; __device__ __forceinline__ void hgrn_passC(Frame& F, const u32x2v* HU, const float* HD) {
;     ...
;     const int tid = F.tid, c = tid & 127, seg = tid >> 7, w = F.wave, lane = F.lane, l15 = lane & 15, lq = lane >> 4;
;     const int tb = w >> 1, wh = w & 1;
;     for (int u = blockIdx.x; u < HG_NU; u += F.G) {
;         const int sc = u & 7, bh = u >> 3, b = bh >> 2, h = bh & 3;
;         _Float16 lfA[16], lfB[16]; bf16 qA_[16], kA_[16], vA_[16], qB_[16], kB_[16], vB_[16];
;         PC_LOAD_LF(lfA, 0);
;         float og[4];
; #pragma unroll
;         for (int n = 0; n < 4; ++n) og[n] = F.onorm_g[h * 128 + 16 * (4 * wh + n) + l15];
;         f32x4 S[8];
; #pragma unroll
;         for (int n = 0; n < 8; ++n) S[n] = (f32x4){0.f, 0.f, 0.f, 0.f};
;         { int p = 0;
;     ...
;           for (; p < sc; p += 3) { const int up = (bh << 3) + p;
;               const bool v1 = p + 1 < sc, v2 = p + 2 < sc; const int u1 = v1 ? up + 1 : up, u2 = v2 ? up + 2 : up;
;               const f32x4 one = (f32x4){1.f, 1.f, 1.f, 1.f}, zero = (f32x4){0.f, 0.f, 0.f, 0.f};
;               const f32x4 da = *(const f32x4*)(HD + (size_t)up * 128 + 16 * w + 4 * lq), db0 = *(const f32x4*)(HD + (size_t)u1 * 128 + 16 * w + 4 * lq), dc0 = *(const f32x4*)(HD + (size_t)u2 * 128 + 16 * w + 4 * lq);
;               const f32x4 db = v1 ? db0 : one, dc = v2 ? dc0 : one;
;               u32x2v ua[8], ub[8], uc[8];
; #pragma unroll
;               for (int n = 0; n < 8; ++n) { ua[n] = HU[(((size_t)up * 8 + w) * 8 + n) * 64 + lane]; ub[n] = HU[(((size_t)u1 * 8 + w) * 8 + n) * 64 + lane]; uc[n] = HU[(((size_t)u2 * 8 + w) * 8 + n) * 64 + lane]; }
; #pragma unroll
;               for (int n = 0; n < 8; ++n) S[n] = ((S[n] * da + HU_F4(ua[n])) * db + (v1 ? HU_F4(ub[n]) : zero)) * dc + (v2 ? HU_F4(uc[n]) : zero); } }
;     ...
;         PC_LOAD_QKV(qA_, kA_, vA_, 0);
	v_add_u32_e32 v9, 0, v12
	s_lshl_b32 s34, s2, 13
	v_add3_u32 v47, s31, v8, v7
	v_lshl_or_b32 v8, s21, 4, v11
	v_sub_u32_e32 v137, v9, v21
	v_add_u32_e32 v142, s34, v9
	v_lshl_add_u32 v150, s21, 12, v9
	v_lshrrev_b32_e32 v9, 3, v8
	v_xor_b32_e32 v39, v9, v39
	v_lshlrev_b32_e32 v38, 7, v132
	v_lshl_add_u32 v40, v40, 4, s31
	v_lshlrev_b32_e32 v42, 7, v147
	v_lshl_add_u32 v39, v39, 4, s31
	v_add_u32_e32 v41, v40, v38
	v_add_u32_e32 v40, v40, v42
	s_cmp_lt_u32 s20, s3
	v_cmp_gt_u32_e64 s[20:21], v8, v132
	v_add_u32_e32 v38, v39, v38
	v_cmp_gt_u32_e64 s[22:23], v8, v147
	v_add_u32_e32 v39, v39, v42
	v_cmp_gt_u32_e64 s[24:25], v8, v148
	v_bitop3_b32 v42, v9, v44, 7 bitop3:0x78
	v_cmp_gt_u32_e64 s[26:27], v8, v149
	v_bitop3_b32 v8, v9, v46, 7 bitop3:0x78
	v_or_b32_e32 v6, s6, v6
	v_lshlrev_b32_e32 v43, 7, v148
	v_lshlrev_b32_e32 v45, 4, v45
	v_lshlrev_b32_e32 v42, 4, v42
	v_lshlrev_b32_e32 v8, 4, v8
	v_add3_u32 v45, s31, v45, v43
	v_add3_u32 v42, s31, v42, v43
	v_add3_u32 v43, s31, v8, v7
	v_or_b32_e32 v8, 1, v6
	v_mov_b32_e32 v9, v69
	s_cselect_b64 s[64:65], -1, 0
	s_lshl_b32 s3, s2, 14
	v_lshlrev_b64 v[76:77], 9, v[8:9]
	v_or_b32_e32 v8, 2, v6
	v_lshlrev_b64 v[78:79], 9, v[8:9]
	v_bitop3_b32 v8, v10, v19, 4 bitop3:0x36
	s_add_i32 s3, s3, s30
	s_mov_b32 s30, s88
	v_readlane_b32 s76, v254, 44
	v_lshlrev_b32_e32 v154, 4, v8
	v_lshlrev_b32_e32 v8, 2, v11
	v_readlane_b32 s88, v254, 56
	v_readlane_b32 s90, v254, 58
	v_readlane_b32 s91, v254, 59
	s_mov_b32 s75, 0
	s_mov_b32 s88, s30
	v_lshl_add_u64 v[8:9], s[90:91], 0, v[8:9]
	s_mov_b64 s[30:31], 0x441e000
	s_add_i32 s34, s34, 0
	v_lshl_add_u64 v[82:83], v[8:9], 0, s[30:31]
	s_lshl_b64 s[30:31], s[74:75], 9
	s_lshl_b32 s74, s2, 7
	v_lshl_or_b32 v70, s2, 6, v11
	s_mov_b64 s[28:29], 0x5200000
	s_add_u32 s2, s68, s30
	v_lshl_add_u64 v[72:73], v[2:3], 0, s[28:29]
	v_lshlrev_b32_e32 v2, 3, v202
	v_mov_b32_e32 v3, v69
	v_add_u32_e32 v19, s3, v143
	v_add_u32_e32 v48, s3, v144
	v_add_u32_e32 v49, s3, v145
	v_add_u32_e32 v50, s3, v146
	s_addc_u32 s3, s69, s31
	v_lshl_add_u64 v[4:5], s[68:69], 0, v[2:3]
	v_bitop3_b32 v7, v10, v18, 7 bitop3:0x78
	v_lshl_add_u64 v[2:3], s[2:3], 0, v[2:3]
	s_mov_b64 s[2:3], 0x4200800
	v_lshlrev_b32_e32 v151, 4, v7
	v_mov_b32_e32 v7, v69
	v_lshl_add_u64 v[88:89], v[2:3], 0, s[2:3]
	s_and_b32 s2, s48, 0xffffffc0
	v_lshlrev_b64 v[74:75], 9, v[6:7]
	v_or_b32_e32 v6, 3, v6
	v_readlane_b32 s50, v255, 7
	s_add_u32 s2, s68, s2
	v_lshlrev_b64 v[80:81], 9, v[6:7]
	v_lshlrev_b32_e32 v6, 1, v11
	v_readlane_b32 s51, v255, 8
	v_readlane_b32 s77, v254, 45
	v_readlane_b32 s78, v254, 46
	v_readlane_b32 s79, v254, 47
	s_addc_u32 s3, s69, 0
	v_add_u32_e32 v16, 0, v15
	s_movk_i32 s6, 0xff
	s_movk_i32 s8, 0x17f
	s_movk_i32 s10, 0x1ff
	v_add_u32_e32 v18, s34, v151
	v_lshlrev_b32_e32 v44, 3, v147
	v_lshlrev_b32_e32 v46, 3, v149
	v_lshl_add_u64 v[6:7], s[50:51], 0, v[6:7]
	v_add_u32_e32 v10, s34, v154
	v_readlane_b32 s80, v254, 48
	v_readlane_b32 s81, v254, 49
	v_lshl_add_u64 v[4:5], v[4:5], 0, s[30:31]
	s_mov_b64 s[34:35], 0x4200000
	s_mov_b64 s[78:79], s[70:71]
	v_lshl_add_u64 v[2:3], s[2:3], 0, v[68:69]
	v_add_u32_e32 v135, s5, v68
	v_cmp_eq_u32_e64 s[4:5], 0, v11
	v_cmp_lt_u32_e64 s[6:7], s6, v0
	v_cmp_lt_u32_e64 s[8:9], s8, v0
	v_cmp_lt_u32_e64 s[10:11], s10, v0
	v_lshlrev_b32_e32 v152, 3, v132
	v_lshlrev_b32_e32 v153, 3, v148
	v_lshl_add_u64 v[84:85], v[4:5], 0, s[34:35]
	v_lshl_add_u64 v[86:87], v[6:7], 0, s[74:75]
	s_mov_b64 s[76:77], s[68:69]
	v_lshl_add_u64 v[90:91], v[2:3], 0, s[28:29]
	s_movk_i32 s69, 0x1000
	s_movk_i32 s70, 0x2000
	s_movk_i32 s71, 0x3000
	s_mov_b32 s80, 0xffff
	v_mov_b32_e32 v155, 0x358637bd
	v_lshlrev_b32_e32 v68, 1, v70
	v_add_u32_e32 v156, v13, v14
	v_add_u32_e32 v157, v16, v23
	v_add_u32_e32 v158, v16, v24
	v_add_u32_e32 v159, v16, v25
	v_add_u32_e32 v160, v16, v26
	v_add_u32_e32 v161, v16, v27
	v_add_u32_e32 v162, v16, v28
	v_add_u32_e32 v163, v16, v29
	v_add_u32_e32 v164, v16, v30
	v_add_u32_e32 v165, v16, v31
	s_waitcnt vmcnt(0)
	v_add_u32_e32 v166, v16, v32
	v_add_u32_e32 v167, v16, v33
	v_add_u32_e32 v168, v16, v34
	v_add_u32_e32 v169, v16, v35
	v_add_u32_e32 v170, v16, v36
	v_add_u32_e32 v171, v16, v22
	v_add_u32_e32 v172, v16, v37
	v_add_u32_e32 v173, 0, v20
	v_add_u32_e32 v174, 0, v17
	v_add_u32_e32 v175, v41, v15
	v_add_u32_e32 v176, v40, v15
	v_add_u32_e32 v177, v45, v15
	v_add_u32_e32 v178, v47, v15
	v_add_u32_e32 v179, v38, v15
	v_add_u32_e32 v180, v39, v15
	v_add_u32_e32 v181, v42, v15
	v_add_u32_e32 v182, v43, v15
	v_add_u32_e32 v183, v18, v21
	v_add_u32_e32 v184, v10, v21
	v_add_u32_e32 v185, v19, v12
	v_add_u32_e32 v186, v48, v12
	v_add_u32_e32 v187, v49, v12
	v_add_u32_e32 v188, v50, v12
	v_add_u32_e32 v189, s43, v44
	v_add_u32_e32 v190, s43, v46
	s_mov_b32 s81, s88
	v_readlane_b32 s82, v254, 50
	v_readlane_b32 s83, v254, 51
	v_readlane_b32 s84, v254, 52
	v_readlane_b32 s85, v254, 53
	v_readlane_b32 s86, v254, 54
	v_readlane_b32 s87, v254, 55
	v_readlane_b32 s89, v254, 57
	s_branch .LBB0_647
